# v121 + FFN-up epilogue row statistics prefetched one tile ahead into spare VGPRs (no vmcnt(0) drain in the epilogue); loop-invariant B base moved to v254 in the FFN-up loop
# baseline (speedup 1.0000x reference)
; #define PG8_STAGE(bufoff, gbase, voff) do { _Pragma("unroll") for (int _i = 0; _i < 2; ++_i) \
;         __builtin_amdgcn_global_load_lds((const unsigned*)((const char*)(gbase) + (voff)[_i]), (PG8_LAS unsigned*)(lds + (bufoff) + ldsw + _i * 8192), 16, 0, 0); } while (0)
; #define PG8_WAIT_V(n) asm volatile("s_waitcnt vmcnt(" #n ")" ::: "memory")
; #define PG8_BAR __builtin_amdgcn_s_barrier()
; template <class Epi, class Sched, bool ALIGN_EPI = false, bool SP2 = false>
; __device__ __forceinline__ void gemm_phase(PG8_LAS unsigned char* lds, const Gemm g, const Sched& S, const Epi& E) {
;     ...
;     for (int i = 0; i < 2; ++i) { int R, C; stage_rc(tid * 16 + i * 8192, R, C); const int Rb = Epi::PERM ? ((R & ~31) + perm32(R & 31)) : R;
;         voffA[i] = (unsigned)(R * BK + C) * 2u; voffB[i] = (unsigned)(Rb * BK + C) * 2u; }
;     ...
;         PG8_STAGE(PG8_SB(0, 0), cB, voffB); PG8_STAGE(PG8_SB(0, 1), cB + hstep, voffB); PG8_STAGE(PG8_SA(0, 0), cA, voffA); PG8_STAGE(PG8_SA(0, 1), cA + hstep, voffA);
;         if (wr == 1) PG8_BAR;
;         PG8_WAIT_V(2); PG8_BAR;
;         PG8_STAGE(PG8_SB(1, 0), cB + kstep, voffB); PG8_STAGE(PG8_SA(1, 0), cA + kstep, voffA); PG8_STAGE(PG8_SB(1, 1), cB + hstep + kstep, voffB);
.LBB0_1346:
	s_andn2_b64 vcc, exec, s[0:1]
	s_cbranch_vccnz .LBB0_1363
	v_mov_b32_e32 v0, v230
	s_cmpk_gt_i32 s58, 0xaff
	v_readfirstlane_b32 s3, v0
	s_cbranch_scc1 .LBB0_1363
	v_lshlrev_b32_e32 v4, 4, v0
	v_add_u32_e32 v2, 0x2000, v4
	s_waitcnt lgkmcnt(0)
	v_ashrrev_i32_e32 v1, 31, v2
	v_lshrrev_b32_e32 v1, 22, v1
	v_add_u32_e32 v1, v2, v1
	v_ashrrev_i32_e32 v1, 10, v1
	v_mul_i32_i24_e32 v3, 0x400, v1
	v_sub_u32_e32 v2, v2, v3
	v_lshrrev_b32_e32 v3, 4, v2
	v_bitop3_b32 v3, v3, v2, 32 bitop3:0x6c
	s_add_u32 s22, s62, 0x6400000
	v_ashrrev_i32_e32 v2, 31, v3
	s_addc_u32 s23, s63, 0
	v_readlane_b32 s0, v255, 9
	v_lshrrev_b32_e32 v2, 26, v2
	s_cmp_eq_u32 s0, 0
	v_add_u32_e32 v5, v3, v2
	v_lshlrev_b32_e32 v6, 3, v1
	s_cselect_b32 s0, 0, 0x2080000
	v_readlane_b32 s1, v255, 10
	v_ashrrev_i32_e32 v2, 6, v5
	v_and_b32_e32 v6, -16, v6
	s_add_u32 s27, s1, s0
	v_readlane_b32 s0, v255, 11
	v_add_u32_e32 v6, v2, v6
	s_addc_u32 s28, s0, 0
	v_and_b32_e32 v7, 3, v2
	s_mov_b32 s0, 0x1ffffe0
	v_lshrrev_b32_e32 v8, 2, v6
	v_lshlrev_b32_e32 v9, 1, v6
	v_and_b32_e32 v5, 0xc0, v5
	v_and_or_b32 v7, v6, s0, v7
	v_and_b32_e32 v8, 4, v8
	v_and_b32_e32 v9, 24, v9
	v_sub_u32_e32 v3, v3, v5
	v_or3_b32 v7, v7, v8, v9
	v_lshlrev_b32_e32 v8, 5, v1
	v_ashrrev_i16_sdwa v3, v237, sext(v3) dst_sel:DWORD dst_unused:UNUSED_PAD src0_sel:DWORD src1_sel:BYTE_0
	v_and_b32_e32 v8, 32, v8
	v_bfe_i32 v3, v3, 0, 16
	v_add_lshl_u32 v5, v8, v3, 1
	v_lshl_add_u32 v144, v7, 7, v5
	v_lshl_add_u32 v146, v6, 7, v5
	v_bfe_i32 v5, v0, 27, 1
	v_lshrrev_b32_e32 v5, 22, v5
	v_add_u32_e32 v5, v4, v5
	v_and_b32_e32 v5, 0xfffffc00, v5
	v_sub_u32_e32 v4, v4, v5
	v_lshrrev_b32_e32 v5, 4, v4
	v_bitop3_b32 v6, v5, v4, 32 bitop3:0x6c
	v_ashrrev_i32_e32 v5, 31, v0
	v_lshrrev_b32_e32 v5, 26, v5
	v_ashrrev_i32_e32 v4, 31, v6
	v_add_u32_e32 v5, v0, v5
	v_lshrrev_b32_e32 v4, 26, v4
	v_ashrrev_i32_e32 v5, 6, v5
	v_add_u32_e32 v7, v6, v4
	v_lshlrev_b32_e32 v8, 3, v5
	v_ashrrev_i32_e32 v4, 6, v7
	v_and_b32_e32 v8, -16, v8
	v_add_u32_e32 v8, v4, v8
	v_and_b32_e32 v9, 3, v4
	s_ashr_i32 s33, s58, 31
	v_and_or_b32 v9, v8, s0, v9
	s_lshr_b32 s0, s33, 29
	s_add_i32 s0, s58, s0
	s_ashr_i32 s6, s3, 6
	s_ashr_i32 s1, s0, 3
	s_and_b32 s0, s0, -8
	s_ashr_i32 s7, s3, 8
	s_lshl_b32 s30, s6, 10
	s_sub_i32 s0, s58, s0
	s_cmp_lt_i32 s0, 0
	s_movk_i32 s2, 0x161
	s_cselect_b32 s2, s2, 0x160
	s_mul_i32 s0, s0, s2
	s_add_i32 s0, s0, s1
	s_mul_hi_i32 s1, s0, 0x2e8ba2e9
	s_lshr_b32 s2, s1, 31
	s_ashr_i32 s1, s1, 5
	s_add_i32 s1, s1, s2
	s_lshl_b32 s4, s1, 3
	s_mulk_i32 s1, 0xb0
	s_sub_i32 s0, s0, s1
	s_bfe_u32 s1, s0, 0x3001c
	s_add_i32 s1, s0, s1
	s_sext_i32_i16 s2, s1
	s_and_b32 s1, s1, 0xfff8
	s_sub_i32 s0, s0, s1
	s_sext_i32_i16 s0, s0
	v_lshrrev_b32_e32 v10, 2, v8
	v_lshlrev_b32_e32 v11, 1, v8
	v_and_b32_e32 v7, 0xc0, v7
	s_lshr_b32 s2, s2, 3
	s_add_i32 s16, s4, s0
	v_and_b32_e32 v10, 4, v10
	v_and_b32_e32 v11, 24, v11
	v_sub_u32_e32 v6, v6, v7
	s_ashr_i32 s17, s16, 31
	s_bfe_i64 s[4:5], s[2:3], 0x100000
	v_or3_b32 v9, v9, v10, v11
	v_lshlrev_b32_e32 v10, 5, v5
	v_ashrrev_i16_sdwa v6, v237, sext(v6) dst_sel:DWORD dst_unused:UNUSED_PAD src0_sel:DWORD src1_sel:BYTE_0
	s_lshl_b64 s[0:1], s[16:17], 19
	s_lshl_b64 s[4:5], s[4:5], 19
	v_and_b32_e32 v10, 32, v10
	v_bfe_i32 v6, v6, 0, 16
	s_add_u32 s20, s27, s4
	v_add_lshl_u32 v7, v10, v6, 1
	s_addc_u32 s21, s28, s5
	s_add_u32 s92, s62, 0x1e500000
	s_addc_u32 s93, s63, 0
	s_lshl_b32 s77, s7, 6
	s_lshl_b32 s91, s16, 8
	s_add_i32 s91, s91, s77
	v_and_or_b32 v232, v230, 15, s91
	v_bfe_u32 v233, v230, 4, 2
	v_lshlrev_b32_e32 v232, 6, v232
	v_lshl_add_u32 v232, v233, 4, v232
	v_add_u32_e32 v233, 0x2000, v232
	global_load_dwordx4 v[208:211], v232, s[92:93]
	global_load_dwordx4 v[212:215], v232, s[92:93] offset:1024
	global_load_dwordx4 v[216:219], v232, s[92:93] offset:2048
	global_load_dwordx4 v[222:225], v232, s[92:93] offset:3072
	global_load_dwordx4 v[226:229], v233, s[92:93]
	global_load_dwordx4 v[240:243], v233, s[92:93] offset:1024
	global_load_dwordx4 v[246:249], v233, s[92:93] offset:2048
	global_load_dwordx4 v[250:253], v233, s[92:93] offset:3072
	s_add_i32 s37, s30, 0
	v_lshl_add_u32 v148, v9, 7, v7
	s_add_i32 m0, s37, 0x10000
	v_lshl_add_u32 v150, v8, 7, v7
	global_load_lds_dwordx4 v148, s[20:21]
	s_add_i32 m0, s37, 0x12000
	s_add_u32 s4, s20, 0x4000
	global_load_lds_dwordx4 v144, s[20:21]
	s_addc_u32 s5, s21, 0
	s_add_i32 m0, s37, 0x14000
	s_mov_b32 s73, s52
	global_load_lds_dwordx4 v148, s[4:5]
	s_add_i32 m0, s37, 0x16000
	s_add_u32 s18, s22, s0
	s_addc_u32 s19, s23, s1
	s_add_i32 s39, s37, 0x2000
	global_load_lds_dwordx4 v144, s[4:5]
	s_mov_b32 m0, s37
	s_add_u32 s0, s18, 0x4000
	global_load_lds_dwordx4 v150, s[18:19]
	s_mov_b32 m0, s39
	s_addc_u32 s1, s19, 0
	s_add_i32 s41, s37, 0x4000
	global_load_lds_dwordx4 v146, s[18:19]
	s_mov_b32 m0, s41
	s_add_i32 s42, s37, 0x6000
	global_load_lds_dwordx4 v150, s[0:1]
	s_mov_b32 m0, s42
	s_cmp_eq_u32 s7, 1
	global_load_lds_dwordx4 v146, s[0:1]
	s_cselect_b64 s[0:1], -1, 0
	s_cmp_lg_u32 s7, 1
	s_cbranch_scc1 .LBB0_1350
	s_barrier

; #define PG8_STAGE(bufoff, gbase, voff) do { _Pragma("unroll") for (int _i = 0; _i < 2; ++_i) \
;         __builtin_amdgcn_global_load_lds((const unsigned*)((const char*)(gbase) + (voff)[_i]), (PG8_LAS unsigned*)(lds + (bufoff) + ldsw + _i * 8192), 16, 0, 0); } while (0)
; #define PG8_LDA(dst, b, h) do { _Pragma("unroll") for (int m = 0; m < 4; ++m) _Pragma("unroll") for (int k = 0; k < 2; ++k) dst[m][k] = *(const PG8_LAS bf16x8*)(lds + PG8_SA(b, h) + aoff + m * 2048 + k * 1024); } while (0)
; #define PG8_LDB(dst, b, h) do { _Pragma("unroll") for (int n = 0; n < 2; ++n) _Pragma("unroll") for (int k = 0; k < 2; ++k) dst[n][k] = *(const PG8_LAS bf16x8*)(lds + PG8_SB(b, h) + boff + n * 2048 + k * 1024); } while (0)
; #define PG8_MMA(ai, bj, At, Bt) do { __builtin_amdgcn_s_setprio(1); _Pragma("unroll") for (int m = 0; m < 4; ++m) _Pragma("unroll") for (int n = 0; n < 2; ++n) _Pragma("unroll") for (int k = 0; k < 2; ++k) \
;         acc[ai][bj][m][n] = __builtin_amdgcn_mfma_f32_16x16x32_bf16(Bt[n][k], At[m][k], acc[ai][bj][m][n], 0, 0, 0); __builtin_amdgcn_s_setprio(0); } while (0)
; #define PG8_WAIT_V(n) asm volatile("s_waitcnt vmcnt(" #n ")" ::: "memory")
; #define PG8_WAIT_L(n) asm volatile("s_waitcnt lgkmcnt(" #n ")" ::: "memory")
; #define PG8_BAR __builtin_amdgcn_s_barrier()
; #define PG8_SCHED __builtin_amdgcn_sched_barrier(0)
; template <class Epi, class Sched, bool ALIGN_EPI = false, bool SP2 = false>
; __device__ __forceinline__ void gemm_phase(PG8_LAS unsigned char* lds, const Gemm g, const Sched& S, const Epi& E) {
;     ...
;         const char* nA = has_next ? (const char*)g.A + (size_t)nxt.pm * tstep : cA; const char* nB = has_next ? (const char*)g.Bt + (size_t)nxt.pn * tstep : cB;
;         for (int t = 0; t < nt; t += 2) {
;             const bool last = (t == nt - 2);
;             const char* a1 = cA + (size_t)(t + 1) * kstep;
;             const char* a2 = last ? nA : cA + (size_t)(t + 2) * kstep; const char* b2 = last ? nB : cB + (size_t)(t + 2) * kstep;
;     ...
;             PG8_LDB(B0, 0, 0); PG8_LDB(B1, 0, 1); PG8_SCHED; PG8_LDA(At, 0, 0); PG8_STAGE(PG8_SA(1, 1), a1 + hstep, voffA);
;             PG8_WAIT_V(8); PG8_WAIT_L(0); PG8_BAR; PG8_MMA(0, 0, At, B0); PG8_MMA(0, 1, At, B1); PG8_BAR; PG8_SCHED;
;             PG8_LDA(At, 0, 1); PG8_STAGE(PG8_SB(0, 0), b2, voffB); PG8_STAGE(PG8_SB(0, 1), b2 + hstep, voffB); PG8_STAGE(PG8_SA(0, 0), a2, voffA);
.LBB0_1355:
	s_ashr_i32 s11, s10, 31
	s_lshl_b64 s[12:13], s[10:11], 19
	s_add_u32 s12, s22, s12
	s_addc_u32 s13, s23, s13
	s_and_b64 s[14:15], s[2:3], exec
	s_cselect_b32 s11, s13, s19
	s_cselect_b32 s40, s12, s18
	s_ashr_i32 s9, s8, 31
	s_lshl_b64 s[14:15], s[8:9], 19
	s_add_u32 s14, s27, s14
	s_addc_u32 s15, s28, s15
	s_and_b64 s[62:63], s[2:3], exec
	s_cselect_b32 s9, s15, s21
	s_cselect_b32 s61, s14, s20
	s_add_u32 s18, s18, 0xc000
	s_addc_u32 s19, s19, 0
	s_add_u32 s66, s20, 0x10000
	v_mov_b32_e32 v0, 0
	s_addc_u32 s67, s21, 0
	s_mov_b32 s68, -2
	v_add_u32_e32 v254, 0x10000, v162
	s_add_u32 s20, s18, 0x4000
	s_addc_u32 s21, s19, 0
	s_cmp_eq_u32 s68, 12
	s_cselect_b32 s64, s40, s20
	s_cselect_b32 s65, s11, s21
	s_cselect_b32 s62, s61, s66
	s_cselect_b32 s63, s9, s67
	s_add_u32 s20, s64, 0x8000
	s_addc_u32 s21, s65, 0
	s_add_i32 s69, 0, 0x10000
	s_add_i32 s72, 0, 0x14000
	ds_read_b128 v[128:131], v254
	ds_read_b128 v[132:135], v254 offset:1024
	ds_read_b128 v[136:139], v254 offset:2048
	ds_read_b128 v[140:143], v254 offset:3072
	ds_read_b128 v[156:159], v254 offset:16384
	ds_read_b128 v[164:167], v254 offset:17408
	ds_read_b128 v[168:171], v254 offset:18432
	ds_read_b128 v[172:175], v254 offset:19456
	s_add_i32 m0, s37, 0xc000
	ds_read_b128 v[176:179], v163
	ds_read_b128 v[180:183], v163 offset:1024
	ds_read_b128 v[184:187], v163 offset:2048
	ds_read_b128 v[188:191], v163 offset:3072
	ds_read_b128 v[192:195], v163 offset:4096
	ds_read_b128 v[196:199], v163 offset:5120
	ds_read_b128 v[200:203], v163 offset:6144
	ds_read_b128 v[204:207], v163 offset:7168
	global_load_lds_dwordx4 v152, s[18:19]
	s_add_i32 m0, s37, 0xe000
	s_nop 0
	global_load_lds_dwordx4 v154, s[18:19]
	s_waitcnt vmcnt(8) lgkmcnt(0)
	s_barrier
	v_mfma_f32_16x16x32_bf16 v[124:127], v[128:131], v[176:179], 0
	v_mfma_f32_16x16x32_bf16 v[120:123], v[136:139], v[176:179], 0
	v_mfma_f32_16x16x32_bf16 v[108:111], v[128:131], v[184:187], 0
	v_mfma_f32_16x16x32_bf16 v[104:107], v[136:139], v[184:187], 0
	v_mfma_f32_16x16x32_bf16 v[92:95], v[128:131], v[192:195], 0
	v_mfma_f32_16x16x32_bf16 v[88:91], v[136:139], v[192:195], 0
	v_mfma_f32_16x16x32_bf16 v[76:79], v[128:131], v[200:203], 0
	v_mfma_f32_16x16x32_bf16 v[72:75], v[136:139], v[200:203], 0
	v_mfma_f32_16x16x32_bf16 v[124:127], v[132:135], v[180:183], v[124:127]
	v_mfma_f32_16x16x32_bf16 v[120:123], v[140:143], v[180:183], v[120:123]
	v_mfma_f32_16x16x32_bf16 v[108:111], v[132:135], v[188:191], v[108:111]
	v_mfma_f32_16x16x32_bf16 v[104:107], v[140:143], v[188:191], v[104:107]
	v_mfma_f32_16x16x32_bf16 v[92:95], v[132:135], v[196:199], v[92:95]
	v_mfma_f32_16x16x32_bf16 v[88:91], v[140:143], v[196:199], v[88:91]
	v_mfma_f32_16x16x32_bf16 v[76:79], v[132:135], v[204:207], v[76:79]
	v_mfma_f32_16x16x32_bf16 v[72:75], v[140:143], v[204:207], v[72:75]
	v_mfma_f32_16x16x32_bf16 v[116:119], v[156:159], v[176:179], 0
	v_mfma_f32_16x16x32_bf16 v[112:115], v[168:171], v[176:179], 0
	v_mfma_f32_16x16x32_bf16 v[100:103], v[156:159], v[184:187], 0
	v_mfma_f32_16x16x32_bf16 v[96:99], v[168:171], v[184:187], 0
	v_mfma_f32_16x16x32_bf16 v[84:87], v[156:159], v[192:195], 0
	v_mfma_f32_16x16x32_bf16 v[80:83], v[168:171], v[192:195], 0
	v_mfma_f32_16x16x32_bf16 v[68:71], v[156:159], v[200:203], 0
	v_mfma_f32_16x16x32_bf16 v[64:67], v[168:171], v[200:203], 0
	v_mfma_f32_16x16x32_bf16 v[116:119], v[164:167], v[180:183], v[116:119]
	v_mfma_f32_16x16x32_bf16 v[112:115], v[172:175], v[180:183], v[112:115]
	v_mfma_f32_16x16x32_bf16 v[100:103], v[164:167], v[188:191], v[100:103]
	v_mfma_f32_16x16x32_bf16 v[96:99], v[172:175], v[188:191], v[96:99]
	v_mfma_f32_16x16x32_bf16 v[84:87], v[164:167], v[196:199], v[84:87]
	v_mfma_f32_16x16x32_bf16 v[80:83], v[172:175], v[196:199], v[80:83]
	v_mfma_f32_16x16x32_bf16 v[68:71], v[164:167], v[204:207], v[68:71]
	v_mfma_f32_16x16x32_bf16 v[64:67], v[172:175], v[204:207], v[64:67]
	s_barrier
	s_add_i32 s69, s69, s30
	s_mov_b32 m0, s69
	ds_read_b128 v[176:179], v163 offset:16384
	ds_read_b128 v[180:183], v163 offset:17408
	ds_read_b128 v[184:187], v163 offset:18432
	ds_read_b128 v[188:191], v163 offset:19456
	ds_read_b128 v[192:195], v163 offset:20480
	ds_read_b128 v[196:199], v163 offset:21504
	ds_read_b128 v[200:203], v163 offset:22528
	ds_read_b128 v[204:207], v163 offset:23552
	global_load_lds_dwordx4 v148, s[62:63]
	s_add_i32 m0, s69, 0x2000
	s_add_u32 s70, s62, 0x4000
	s_addc_u32 s71, s63, 0
	s_add_i32 s69, s72, s30
	global_load_lds_dwordx4 v144, s[62:63]
	s_mov_b32 m0, s69
	s_nop 0
	global_load_lds_dwordx4 v148, s[70:71]
	s_add_i32 m0, s69, 0x2000
	s_nop 0
	global_load_lds_dwordx4 v144, s[70:71]
	s_mov_b32 m0, s37
	s_nop 0
	global_load_lds_dwordx4 v150, s[64:65]
	s_mov_b32 m0, s39
	s_nop 0
	global_load_lds_dwordx4 v146, s[64:65]
	s_waitcnt vmcnt(8) lgkmcnt(0)
	s_barrier
; #define PG8_STAGE(bufoff, gbase, voff) do { _Pragma("unroll") for (int _i = 0; _i < 2; ++_i) \
;         __builtin_amdgcn_global_load_lds((const unsigned*)((const char*)(gbase) + (voff)[_i]), (PG8_LAS unsigned*)(lds + (bufoff) + ldsw + _i * 8192), 16, 0, 0); } while (0)
; #define PG8_LDA(dst, b, h) do { _Pragma("unroll") for (int m = 0; m < 4; ++m) _Pragma("unroll") for (int k = 0; k < 2; ++k) dst[m][k] = *(const PG8_LAS bf16x8*)(lds + PG8_SA(b, h) + aoff + m * 2048 + k * 1024); } while (0)
; #define PG8_LDB(dst, b, h) do { _Pragma("unroll") for (int n = 0; n < 2; ++n) _Pragma("unroll") for (int k = 0; k < 2; ++k) dst[n][k] = *(const PG8_LAS bf16x8*)(lds + PG8_SB(b, h) + boff + n * 2048 + k * 1024); } while (0)
; #define PG8_MMA(ai, bj, At, Bt) do { __builtin_amdgcn_s_setprio(1); _Pragma("unroll") for (int m = 0; m < 4; ++m) _Pragma("unroll") for (int n = 0; n < 2; ++n) _Pragma("unroll") for (int k = 0; k < 2; ++k) \
;         acc[ai][bj][m][n] = __builtin_amdgcn_mfma_f32_16x16x32_bf16(Bt[n][k], At[m][k], acc[ai][bj][m][n], 0, 0, 0); __builtin_amdgcn_s_setprio(0); } while (0)
; #define PG8_WAIT_V(n) asm volatile("s_waitcnt vmcnt(" #n ")" ::: "memory")
; #define PG8_WAIT_L(n) asm volatile("s_waitcnt lgkmcnt(" #n ")" ::: "memory")
; #define PG8_BAR __builtin_amdgcn_s_barrier()
; #define PG8_SCHED __builtin_amdgcn_sched_barrier(0)
; template <class Epi, class Sched, bool ALIGN_EPI = false, bool SP2 = false>
; __device__ __forceinline__ void gemm_phase(PG8_LAS unsigned char* lds, const Gemm g, const Sched& S, const Epi& E) {
;     ...
;             PG8_WAIT_V(8); PG8_WAIT_L(0); PG8_BAR; PG8_MMA(1, 0, At, B0); PG8_MMA(1, 1, At, B1); PG8_BAR; PG8_SCHED;
;             PG8_LDB(B0, 1, 0); PG8_LDB(B1, 1, 1); PG8_SCHED; PG8_LDA(At, 1, 0); PG8_STAGE(PG8_SA(0, 1), a2 + hstep, voffA);
;             PG8_WAIT_V(8); PG8_WAIT_L(0); PG8_BAR; PG8_MMA(0, 0, At, B0); PG8_MMA(0, 1, At, B1); PG8_BAR; PG8_SCHED;
	v_mfma_f32_16x16x32_bf16 v[60:63], v[128:131], v[176:179], 0
	v_mfma_f32_16x16x32_bf16 v[56:59], v[136:139], v[176:179], 0
	v_mfma_f32_16x16x32_bf16 v[44:47], v[128:131], v[184:187], 0
	v_mfma_f32_16x16x32_bf16 v[40:43], v[136:139], v[184:187], 0
	v_mfma_f32_16x16x32_bf16 v[28:31], v[128:131], v[192:195], 0
	v_mfma_f32_16x16x32_bf16 v[24:27], v[136:139], v[192:195], 0
	v_mfma_f32_16x16x32_bf16 v[12:15], v[128:131], v[200:203], 0
	v_mfma_f32_16x16x32_bf16 v[8:11], v[136:139], v[200:203], 0
	v_mfma_f32_16x16x32_bf16 v[60:63], v[132:135], v[180:183], v[60:63]
	v_mfma_f32_16x16x32_bf16 v[56:59], v[140:143], v[180:183], v[56:59]
	v_mfma_f32_16x16x32_bf16 v[44:47], v[132:135], v[188:191], v[44:47]
	v_mfma_f32_16x16x32_bf16 v[40:43], v[140:143], v[188:191], v[40:43]
	v_mfma_f32_16x16x32_bf16 v[28:31], v[132:135], v[196:199], v[28:31]
	v_mfma_f32_16x16x32_bf16 v[24:27], v[140:143], v[196:199], v[24:27]
	v_mfma_f32_16x16x32_bf16 v[12:15], v[132:135], v[204:207], v[12:15]
	v_mfma_f32_16x16x32_bf16 v[8:11], v[140:143], v[204:207], v[8:11]
	v_mfma_f32_16x16x32_bf16 v[52:55], v[156:159], v[176:179], 0
	v_mfma_f32_16x16x32_bf16 v[48:51], v[168:171], v[176:179], 0
	v_mfma_f32_16x16x32_bf16 v[36:39], v[156:159], v[184:187], 0
	v_mfma_f32_16x16x32_bf16 v[32:35], v[168:171], v[184:187], 0
	v_mfma_f32_16x16x32_bf16 v[20:23], v[156:159], v[192:195], 0
	v_mfma_f32_16x16x32_bf16 v[16:19], v[168:171], v[192:195], 0
	v_mfma_f32_16x16x32_bf16 v[4:7], v[156:159], v[200:203], 0
	v_mfma_f32_16x16x32_bf16 v[0:3], v[168:171], v[200:203], 0
	v_mfma_f32_16x16x32_bf16 v[52:55], v[164:167], v[180:183], v[52:55]
	v_mfma_f32_16x16x32_bf16 v[48:51], v[172:175], v[180:183], v[48:51]
	v_mfma_f32_16x16x32_bf16 v[36:39], v[164:167], v[188:191], v[36:39]
	v_mfma_f32_16x16x32_bf16 v[32:35], v[172:175], v[188:191], v[32:35]
	v_mfma_f32_16x16x32_bf16 v[20:23], v[164:167], v[196:199], v[20:23]
	v_mfma_f32_16x16x32_bf16 v[16:19], v[172:175], v[196:199], v[16:19]
	v_mfma_f32_16x16x32_bf16 v[4:7], v[164:167], v[204:207], v[4:7]
	v_mfma_f32_16x16x32_bf16 v[0:3], v[172:175], v[204:207], v[0:3]
	s_barrier
	s_add_i32 s69, 0, 0x18000
	s_add_i32 s70, 0, 0x1c000
	ds_read_b128 v[128:131], v254 offset:32768
	ds_read_b128 v[132:135], v254 offset:33792
	ds_read_b128 v[136:139], v254 offset:34816
	ds_read_b128 v[140:143], v254 offset:35840
	ds_read_b128 v[156:159], v254 offset:49152
	ds_read_b128 v[164:167], v254 offset:50176
	ds_read_b128 v[168:171], v254 offset:51200
	ds_read_b128 v[172:175], v254 offset:52224
	s_add_u32 s64, s64, 0x4000
	s_addc_u32 s65, s65, 0
	s_mov_b32 m0, s41
	ds_read_b128 v[176:179], v163 offset:32768
	ds_read_b128 v[180:183], v163 offset:33792
	ds_read_b128 v[184:187], v163 offset:34816
	ds_read_b128 v[188:191], v163 offset:35840
	ds_read_b128 v[192:195], v163 offset:36864
	ds_read_b128 v[196:199], v163 offset:37888
	ds_read_b128 v[200:203], v163 offset:38912
	ds_read_b128 v[204:207], v163 offset:39936
	global_load_lds_dwordx4 v150, s[64:65]
	s_mov_b32 m0, s42
	s_nop 0
	global_load_lds_dwordx4 v146, s[64:65]
	s_waitcnt vmcnt(8) lgkmcnt(0)
	s_barrier
	v_mfma_f32_16x16x32_bf16 v[124:127], v[128:131], v[176:179], v[124:127]
	v_mfma_f32_16x16x32_bf16 v[120:123], v[136:139], v[176:179], v[120:123]
	v_mfma_f32_16x16x32_bf16 v[108:111], v[128:131], v[184:187], v[108:111]
	v_mfma_f32_16x16x32_bf16 v[104:107], v[136:139], v[184:187], v[104:107]
	v_mfma_f32_16x16x32_bf16 v[92:95], v[128:131], v[192:195], v[92:95]
	v_mfma_f32_16x16x32_bf16 v[88:91], v[136:139], v[192:195], v[88:91]
	v_mfma_f32_16x16x32_bf16 v[76:79], v[128:131], v[200:203], v[76:79]
	v_mfma_f32_16x16x32_bf16 v[72:75], v[136:139], v[200:203], v[72:75]
	v_mfma_f32_16x16x32_bf16 v[124:127], v[132:135], v[180:183], v[124:127]
	v_mfma_f32_16x16x32_bf16 v[120:123], v[140:143], v[180:183], v[120:123]
	v_mfma_f32_16x16x32_bf16 v[108:111], v[132:135], v[188:191], v[108:111]
	v_mfma_f32_16x16x32_bf16 v[104:107], v[140:143], v[188:191], v[104:107]
	v_mfma_f32_16x16x32_bf16 v[92:95], v[132:135], v[196:199], v[92:95]
	v_mfma_f32_16x16x32_bf16 v[88:91], v[140:143], v[196:199], v[88:91]
	v_mfma_f32_16x16x32_bf16 v[76:79], v[132:135], v[204:207], v[76:79]
	v_mfma_f32_16x16x32_bf16 v[72:75], v[140:143], v[204:207], v[72:75]
	v_mfma_f32_16x16x32_bf16 v[116:119], v[156:159], v[176:179], v[116:119]
	v_mfma_f32_16x16x32_bf16 v[112:115], v[168:171], v[176:179], v[112:115]
	v_mfma_f32_16x16x32_bf16 v[100:103], v[156:159], v[184:187], v[100:103]
	v_mfma_f32_16x16x32_bf16 v[96:99], v[168:171], v[184:187], v[96:99]
	v_mfma_f32_16x16x32_bf16 v[84:87], v[156:159], v[192:195], v[84:87]
	v_mfma_f32_16x16x32_bf16 v[80:83], v[168:171], v[192:195], v[80:83]
	v_mfma_f32_16x16x32_bf16 v[68:71], v[156:159], v[200:203], v[68:71]
	v_mfma_f32_16x16x32_bf16 v[64:67], v[168:171], v[200:203], v[64:67]
	v_mfma_f32_16x16x32_bf16 v[116:119], v[164:167], v[180:183], v[116:119]
	v_mfma_f32_16x16x32_bf16 v[112:115], v[172:175], v[180:183], v[112:115]
	v_mfma_f32_16x16x32_bf16 v[100:103], v[164:167], v[188:191], v[100:103]
	v_mfma_f32_16x16x32_bf16 v[96:99], v[172:175], v[188:191], v[96:99]
	v_mfma_f32_16x16x32_bf16 v[84:87], v[164:167], v[196:199], v[84:87]
	v_mfma_f32_16x16x32_bf16 v[80:83], v[172:175], v[196:199], v[80:83]
	v_mfma_f32_16x16x32_bf16 v[68:71], v[164:167], v[204:207], v[68:71]
	v_mfma_f32_16x16x32_bf16 v[64:67], v[172:175], v[204:207], v[64:67]
	s_barrier
; #define PG8_STAGE(bufoff, gbase, voff) do { _Pragma("unroll") for (int _i = 0; _i < 2; ++_i) \
;         __builtin_amdgcn_global_load_lds((const unsigned*)((const char*)(gbase) + (voff)[_i]), (PG8_LAS unsigned*)(lds + (bufoff) + ldsw + _i * 8192), 16, 0, 0); } while (0)
; #define PG8_LDA(dst, b, h) do { _Pragma("unroll") for (int m = 0; m < 4; ++m) _Pragma("unroll") for (int k = 0; k < 2; ++k) dst[m][k] = *(const PG8_LAS bf16x8*)(lds + PG8_SA(b, h) + aoff + m * 2048 + k * 1024); } while (0)
; #define PG8_LDB(dst, b, h) do { _Pragma("unroll") for (int n = 0; n < 2; ++n) _Pragma("unroll") for (int k = 0; k < 2; ++k) dst[n][k] = *(const PG8_LAS bf16x8*)(lds + PG8_SB(b, h) + boff + n * 2048 + k * 1024); } while (0)
; #define PG8_MMA(ai, bj, At, Bt) do { __builtin_amdgcn_s_setprio(1); _Pragma("unroll") for (int m = 0; m < 4; ++m) _Pragma("unroll") for (int n = 0; n < 2; ++n) _Pragma("unroll") for (int k = 0; k < 2; ++k) \
;         acc[ai][bj][m][n] = __builtin_amdgcn_mfma_f32_16x16x32_bf16(Bt[n][k], At[m][k], acc[ai][bj][m][n], 0, 0, 0); __builtin_amdgcn_s_setprio(0); } while (0)
; #define PG8_WAIT_V(n) asm volatile("s_waitcnt vmcnt(" #n ")" ::: "memory")
; #define PG8_WAIT_L(n) asm volatile("s_waitcnt lgkmcnt(" #n ")" ::: "memory")
; #define PG8_BAR __builtin_amdgcn_s_barrier()
; #define PG8_SCHED __builtin_amdgcn_sched_barrier(0)
; template <class Epi, class Sched, bool ALIGN_EPI = false, bool SP2 = false>
; __device__ __forceinline__ void gemm_phase(PG8_LAS unsigned char* lds, const Gemm g, const Sched& S, const Epi& E) {
;     ...
;             PG8_LDB(B0, 0, 0); PG8_LDB(B1, 0, 1); PG8_SCHED; PG8_LDA(At, 0, 0); PG8_STAGE(PG8_SA(1, 1), a1 + hstep, voffA);
;             PG8_WAIT_V(8); PG8_WAIT_L(0); PG8_BAR; PG8_MMA(0, 0, At, B0); PG8_MMA(0, 1, At, B1); PG8_BAR; PG8_SCHED;
;     ...
;             PG8_LDA(At, 1, 1); PG8_STAGE(PG8_SB(1, 0), b3, voffB); PG8_STAGE(PG8_SB(1, 1), b3 + hstep, voffB); PG8_STAGE(PG8_SA(1, 0), a3, voffA);
;             PG8_WAIT_V(8); PG8_WAIT_L(0); PG8_BAR; PG8_MMA(1, 0, At, B0); PG8_MMA(1, 1, At, B1); PG8_BAR; PG8_SCHED;
	s_add_u32 s64, s62, 0x8000
	s_addc_u32 s65, s63, 0
	s_add_i32 s69, s69, s30
	s_mov_b32 m0, s69
	ds_read_b128 v[176:179], v163 offset:49152
	ds_read_b128 v[180:183], v163 offset:50176
	ds_read_b128 v[184:187], v163 offset:51200
	ds_read_b128 v[188:191], v163 offset:52224
	ds_read_b128 v[192:195], v163 offset:53248
	ds_read_b128 v[196:199], v163 offset:54272
	ds_read_b128 v[200:203], v163 offset:55296
	ds_read_b128 v[204:207], v163 offset:56320
	global_load_lds_dwordx4 v148, s[64:65]
	s_add_i32 m0, s69, 0x2000
	s_add_u32 s62, s62, 0xc000
	s_addc_u32 s63, s63, 0
	s_add_i32 s91, s70, s30
	global_load_lds_dwordx4 v144, s[64:65]
	s_mov_b32 m0, s91
	s_nop 0
	global_load_lds_dwordx4 v148, s[62:63]
	s_add_i32 m0, s91, 0x2000
	s_nop 0
	global_load_lds_dwordx4 v144, s[62:63]
	s_mov_b32 m0, s54
	s_nop 0
	global_load_lds_dwordx4 v150, s[20:21]
	s_mov_b32 m0, s55
	s_nop 0
	global_load_lds_dwordx4 v146, s[20:21]
	s_waitcnt vmcnt(8) lgkmcnt(0)
	s_barrier
	v_mfma_f32_16x16x32_bf16 v[60:63], v[128:131], v[176:179], v[60:63]
	v_mfma_f32_16x16x32_bf16 v[56:59], v[136:139], v[176:179], v[56:59]
	v_mfma_f32_16x16x32_bf16 v[44:47], v[128:131], v[184:187], v[44:47]
	v_mfma_f32_16x16x32_bf16 v[40:43], v[136:139], v[184:187], v[40:43]
	v_mfma_f32_16x16x32_bf16 v[28:31], v[128:131], v[192:195], v[28:31]
	v_mfma_f32_16x16x32_bf16 v[24:27], v[136:139], v[192:195], v[24:27]
	v_mfma_f32_16x16x32_bf16 v[12:15], v[128:131], v[200:203], v[12:15]
	v_mfma_f32_16x16x32_bf16 v[8:11], v[136:139], v[200:203], v[8:11]
	v_mfma_f32_16x16x32_bf16 v[60:63], v[132:135], v[180:183], v[60:63]
	v_mfma_f32_16x16x32_bf16 v[56:59], v[140:143], v[180:183], v[56:59]
	v_mfma_f32_16x16x32_bf16 v[44:47], v[132:135], v[188:191], v[44:47]
	v_mfma_f32_16x16x32_bf16 v[40:43], v[140:143], v[188:191], v[40:43]
	v_mfma_f32_16x16x32_bf16 v[28:31], v[132:135], v[196:199], v[28:31]
	v_mfma_f32_16x16x32_bf16 v[24:27], v[140:143], v[196:199], v[24:27]
	v_mfma_f32_16x16x32_bf16 v[12:15], v[132:135], v[204:207], v[12:15]
	v_mfma_f32_16x16x32_bf16 v[8:11], v[140:143], v[204:207], v[8:11]
	v_mfma_f32_16x16x32_bf16 v[52:55], v[156:159], v[176:179], v[52:55]
	v_mfma_f32_16x16x32_bf16 v[48:51], v[168:171], v[176:179], v[48:51]
	v_mfma_f32_16x16x32_bf16 v[36:39], v[156:159], v[184:187], v[36:39]
	v_mfma_f32_16x16x32_bf16 v[32:35], v[168:171], v[184:187], v[32:35]
	v_mfma_f32_16x16x32_bf16 v[20:23], v[156:159], v[192:195], v[20:23]
	v_mfma_f32_16x16x32_bf16 v[16:19], v[168:171], v[192:195], v[16:19]
	v_mfma_f32_16x16x32_bf16 v[4:7], v[156:159], v[200:203], v[4:7]
	v_mfma_f32_16x16x32_bf16 v[0:3], v[168:171], v[200:203], v[0:3]
	v_mfma_f32_16x16x32_bf16 v[52:55], v[164:167], v[180:183], v[52:55]
	v_mfma_f32_16x16x32_bf16 v[48:51], v[172:175], v[180:183], v[48:51]
	v_mfma_f32_16x16x32_bf16 v[36:39], v[164:167], v[188:191], v[36:39]
	v_mfma_f32_16x16x32_bf16 v[32:35], v[172:175], v[188:191], v[32:35]
	v_mfma_f32_16x16x32_bf16 v[20:23], v[164:167], v[196:199], v[20:23]
	v_mfma_f32_16x16x32_bf16 v[16:19], v[172:175], v[196:199], v[16:19]
	v_mfma_f32_16x16x32_bf16 v[4:7], v[164:167], v[204:207], v[4:7]
	v_mfma_f32_16x16x32_bf16 v[0:3], v[172:175], v[204:207], v[0:3]
	s_barrier
	s_add_i32 s68, s68, 2
	s_add_u32 s18, s18, 0x10000
	s_addc_u32 s19, s19, 0
	s_add_u32 s66, s66, 0x10000
	s_addc_u32 s67, s67, 0
	s_cmp_gt_u32 s68, 13
.LBB0_1356:
	s_add_u32 s20, s18, 0x4000
	s_addc_u32 s21, s19, 0
	s_cmp_eq_u32 s68, 12
	s_cselect_b32 s64, s40, s20
	s_cselect_b32 s65, s11, s21
	s_cselect_b32 s62, s61, s66
	s_cselect_b32 s63, s9, s67
	s_add_u32 s20, s64, 0x8000
	s_addc_u32 s21, s65, 0
	s_add_i32 s69, 0, 0x10000
	s_add_i32 s72, 0, 0x14000
	ds_read_b128 v[128:131], v254
	ds_read_b128 v[132:135], v254 offset:1024
	ds_read_b128 v[136:139], v254 offset:2048
	ds_read_b128 v[140:143], v254 offset:3072
	ds_read_b128 v[156:159], v254 offset:16384
	ds_read_b128 v[164:167], v254 offset:17408
	ds_read_b128 v[168:171], v254 offset:18432
	ds_read_b128 v[172:175], v254 offset:19456
	s_add_i32 m0, s37, 0xc000
	ds_read_b128 v[176:179], v163
	ds_read_b128 v[180:183], v163 offset:1024
	ds_read_b128 v[184:187], v163 offset:2048
	ds_read_b128 v[188:191], v163 offset:3072
	ds_read_b128 v[192:195], v163 offset:4096
	ds_read_b128 v[196:199], v163 offset:5120
	ds_read_b128 v[200:203], v163 offset:6144
	ds_read_b128 v[204:207], v163 offset:7168
	global_load_lds_dwordx4 v152, s[18:19]
	s_add_i32 m0, s37, 0xe000
	s_nop 0
	global_load_lds_dwordx4 v154, s[18:19]
	s_waitcnt vmcnt(8) lgkmcnt(0)
	s_barrier
	v_mfma_f32_16x16x32_bf16 v[124:127], v[128:131], v[176:179], v[124:127]
	v_mfma_f32_16x16x32_bf16 v[120:123], v[136:139], v[176:179], v[120:123]
	v_mfma_f32_16x16x32_bf16 v[108:111], v[128:131], v[184:187], v[108:111]
	v_mfma_f32_16x16x32_bf16 v[104:107], v[136:139], v[184:187], v[104:107]
	v_mfma_f32_16x16x32_bf16 v[92:95], v[128:131], v[192:195], v[92:95]
	v_mfma_f32_16x16x32_bf16 v[88:91], v[136:139], v[192:195], v[88:91]
	v_mfma_f32_16x16x32_bf16 v[76:79], v[128:131], v[200:203], v[76:79]
	v_mfma_f32_16x16x32_bf16 v[72:75], v[136:139], v[200:203], v[72:75]
	v_mfma_f32_16x16x32_bf16 v[124:127], v[132:135], v[180:183], v[124:127]
	v_mfma_f32_16x16x32_bf16 v[120:123], v[140:143], v[180:183], v[120:123]
	v_mfma_f32_16x16x32_bf16 v[108:111], v[132:135], v[188:191], v[108:111]
	v_mfma_f32_16x16x32_bf16 v[104:107], v[140:143], v[188:191], v[104:107]
	v_mfma_f32_16x16x32_bf16 v[92:95], v[132:135], v[196:199], v[92:95]
	v_mfma_f32_16x16x32_bf16 v[88:91], v[140:143], v[196:199], v[88:91]
	v_mfma_f32_16x16x32_bf16 v[76:79], v[132:135], v[204:207], v[76:79]
	v_mfma_f32_16x16x32_bf16 v[72:75], v[140:143], v[204:207], v[72:75]
	v_mfma_f32_16x16x32_bf16 v[116:119], v[156:159], v[176:179], v[116:119]
	v_mfma_f32_16x16x32_bf16 v[112:115], v[168:171], v[176:179], v[112:115]
	v_mfma_f32_16x16x32_bf16 v[100:103], v[156:159], v[184:187], v[100:103]
	v_mfma_f32_16x16x32_bf16 v[96:99], v[168:171], v[184:187], v[96:99]
	v_mfma_f32_16x16x32_bf16 v[84:87], v[156:159], v[192:195], v[84:87]
	v_mfma_f32_16x16x32_bf16 v[80:83], v[168:171], v[192:195], v[80:83]
	v_mfma_f32_16x16x32_bf16 v[68:71], v[156:159], v[200:203], v[68:71]
	v_mfma_f32_16x16x32_bf16 v[64:67], v[168:171], v[200:203], v[64:67]
	v_mfma_f32_16x16x32_bf16 v[116:119], v[164:167], v[180:183], v[116:119]
	v_mfma_f32_16x16x32_bf16 v[112:115], v[172:175], v[180:183], v[112:115]
	v_mfma_f32_16x16x32_bf16 v[100:103], v[164:167], v[188:191], v[100:103]
	v_mfma_f32_16x16x32_bf16 v[96:99], v[172:175], v[188:191], v[96:99]
	v_mfma_f32_16x16x32_bf16 v[84:87], v[164:167], v[196:199], v[84:87]
	v_mfma_f32_16x16x32_bf16 v[80:83], v[172:175], v[196:199], v[80:83]
	v_mfma_f32_16x16x32_bf16 v[68:71], v[164:167], v[204:207], v[68:71]
	v_mfma_f32_16x16x32_bf16 v[64:67], v[172:175], v[204:207], v[64:67]
	s_barrier
; #define PG8_STAGE(bufoff, gbase, voff) do { _Pragma("unroll") for (int _i = 0; _i < 2; ++_i) \
;         __builtin_amdgcn_global_load_lds((const unsigned*)((const char*)(gbase) + (voff)[_i]), (PG8_LAS unsigned*)(lds + (bufoff) + ldsw + _i * 8192), 16, 0, 0); } while (0)
; #define PG8_LDA(dst, b, h) do { _Pragma("unroll") for (int m = 0; m < 4; ++m) _Pragma("unroll") for (int k = 0; k < 2; ++k) dst[m][k] = *(const PG8_LAS bf16x8*)(lds + PG8_SA(b, h) + aoff + m * 2048 + k * 1024); } while (0)
; #define PG8_LDB(dst, b, h) do { _Pragma("unroll") for (int n = 0; n < 2; ++n) _Pragma("unroll") for (int k = 0; k < 2; ++k) dst[n][k] = *(const PG8_LAS bf16x8*)(lds + PG8_SB(b, h) + boff + n * 2048 + k * 1024); } while (0)
; #define PG8_MMA(ai, bj, At, Bt) do { __builtin_amdgcn_s_setprio(1); _Pragma("unroll") for (int m = 0; m < 4; ++m) _Pragma("unroll") for (int n = 0; n < 2; ++n) _Pragma("unroll") for (int k = 0; k < 2; ++k) \
;         acc[ai][bj][m][n] = __builtin_amdgcn_mfma_f32_16x16x32_bf16(Bt[n][k], At[m][k], acc[ai][bj][m][n], 0, 0, 0); __builtin_amdgcn_s_setprio(0); } while (0)
; #define PG8_WAIT_V(n) asm volatile("s_waitcnt vmcnt(" #n ")" ::: "memory")
; #define PG8_WAIT_L(n) asm volatile("s_waitcnt lgkmcnt(" #n ")" ::: "memory")
; #define PG8_BAR __builtin_amdgcn_s_barrier()
; #define PG8_SCHED __builtin_amdgcn_sched_barrier(0)
; template <class Epi, class Sched, bool ALIGN_EPI = false, bool SP2 = false>
; __device__ __forceinline__ void gemm_phase(PG8_LAS unsigned char* lds, const Gemm g, const Sched& S, const Epi& E) {
;     ...
;             PG8_WAIT_V(8); PG8_WAIT_L(0); PG8_BAR; PG8_MMA(0, 0, At, B0); PG8_MMA(0, 1, At, B1); PG8_BAR; PG8_SCHED;
;             PG8_LDA(At, 0, 1); PG8_STAGE(PG8_SB(0, 0), b2, voffB); PG8_STAGE(PG8_SB(0, 1), b2 + hstep, voffB); PG8_STAGE(PG8_SA(0, 0), a2, voffA);
;             PG8_WAIT_V(8); PG8_WAIT_L(0); PG8_BAR; PG8_MMA(1, 0, At, B0); PG8_MMA(1, 1, At, B1); PG8_BAR; PG8_SCHED;
;             PG8_LDB(B0, 1, 0); PG8_LDB(B1, 1, 1); PG8_SCHED; PG8_LDA(At, 1, 0); PG8_STAGE(PG8_SA(0, 1), a2 + hstep, voffA);
;             PG8_WAIT_V(8); PG8_WAIT_L(0); PG8_BAR; PG8_MMA(0, 0, At, B0); PG8_MMA(0, 1, At, B1); PG8_BAR; PG8_SCHED;
	s_add_i32 s69, s69, s30
	s_mov_b32 m0, s69
	ds_read_b128 v[176:179], v163 offset:16384
	ds_read_b128 v[180:183], v163 offset:17408
	ds_read_b128 v[184:187], v163 offset:18432
	ds_read_b128 v[188:191], v163 offset:19456
	ds_read_b128 v[192:195], v163 offset:20480
	ds_read_b128 v[196:199], v163 offset:21504
	ds_read_b128 v[200:203], v163 offset:22528
	ds_read_b128 v[204:207], v163 offset:23552
	global_load_lds_dwordx4 v148, s[62:63]
	s_add_i32 m0, s69, 0x2000
	s_add_u32 s70, s62, 0x4000
	s_addc_u32 s71, s63, 0
	s_add_i32 s69, s72, s30
	global_load_lds_dwordx4 v144, s[62:63]
	s_mov_b32 m0, s69
	s_nop 0
	global_load_lds_dwordx4 v148, s[70:71]
	s_add_i32 m0, s69, 0x2000
	s_nop 0
	global_load_lds_dwordx4 v144, s[70:71]
	s_mov_b32 m0, s37
	s_nop 0
	global_load_lds_dwordx4 v150, s[64:65]
	s_mov_b32 m0, s39
	s_nop 0
	global_load_lds_dwordx4 v146, s[64:65]
	s_waitcnt vmcnt(8) lgkmcnt(0)
	s_barrier
	v_mfma_f32_16x16x32_bf16 v[60:63], v[128:131], v[176:179], v[60:63]
	v_mfma_f32_16x16x32_bf16 v[56:59], v[136:139], v[176:179], v[56:59]
	v_mfma_f32_16x16x32_bf16 v[44:47], v[128:131], v[184:187], v[44:47]
	v_mfma_f32_16x16x32_bf16 v[40:43], v[136:139], v[184:187], v[40:43]
	v_mfma_f32_16x16x32_bf16 v[28:31], v[128:131], v[192:195], v[28:31]
	v_mfma_f32_16x16x32_bf16 v[24:27], v[136:139], v[192:195], v[24:27]
	v_mfma_f32_16x16x32_bf16 v[12:15], v[128:131], v[200:203], v[12:15]
	v_mfma_f32_16x16x32_bf16 v[8:11], v[136:139], v[200:203], v[8:11]
	v_mfma_f32_16x16x32_bf16 v[60:63], v[132:135], v[180:183], v[60:63]
	v_mfma_f32_16x16x32_bf16 v[56:59], v[140:143], v[180:183], v[56:59]
	v_mfma_f32_16x16x32_bf16 v[44:47], v[132:135], v[188:191], v[44:47]
	v_mfma_f32_16x16x32_bf16 v[40:43], v[140:143], v[188:191], v[40:43]
	v_mfma_f32_16x16x32_bf16 v[28:31], v[132:135], v[196:199], v[28:31]
	v_mfma_f32_16x16x32_bf16 v[24:27], v[140:143], v[196:199], v[24:27]
	v_mfma_f32_16x16x32_bf16 v[12:15], v[132:135], v[204:207], v[12:15]
	v_mfma_f32_16x16x32_bf16 v[8:11], v[140:143], v[204:207], v[8:11]
	v_mfma_f32_16x16x32_bf16 v[52:55], v[156:159], v[176:179], v[52:55]
	v_mfma_f32_16x16x32_bf16 v[48:51], v[168:171], v[176:179], v[48:51]
	v_mfma_f32_16x16x32_bf16 v[36:39], v[156:159], v[184:187], v[36:39]
	v_mfma_f32_16x16x32_bf16 v[32:35], v[168:171], v[184:187], v[32:35]
	v_mfma_f32_16x16x32_bf16 v[20:23], v[156:159], v[192:195], v[20:23]
	v_mfma_f32_16x16x32_bf16 v[16:19], v[168:171], v[192:195], v[16:19]
	v_mfma_f32_16x16x32_bf16 v[4:7], v[156:159], v[200:203], v[4:7]
	v_mfma_f32_16x16x32_bf16 v[0:3], v[168:171], v[200:203], v[0:3]
	v_mfma_f32_16x16x32_bf16 v[52:55], v[164:167], v[180:183], v[52:55]
	v_mfma_f32_16x16x32_bf16 v[48:51], v[172:175], v[180:183], v[48:51]
	v_mfma_f32_16x16x32_bf16 v[36:39], v[164:167], v[188:191], v[36:39]
	v_mfma_f32_16x16x32_bf16 v[32:35], v[172:175], v[188:191], v[32:35]
	v_mfma_f32_16x16x32_bf16 v[20:23], v[164:167], v[196:199], v[20:23]
	v_mfma_f32_16x16x32_bf16 v[16:19], v[172:175], v[196:199], v[16:19]
	v_mfma_f32_16x16x32_bf16 v[4:7], v[164:167], v[204:207], v[4:7]
	v_mfma_f32_16x16x32_bf16 v[0:3], v[172:175], v[204:207], v[0:3]
	s_barrier
	s_add_i32 s69, 0, 0x18000
	s_add_i32 s70, 0, 0x1c000
	ds_read_b128 v[128:131], v254 offset:32768
	ds_read_b128 v[132:135], v254 offset:33792
	ds_read_b128 v[136:139], v254 offset:34816
	ds_read_b128 v[140:143], v254 offset:35840
	ds_read_b128 v[156:159], v254 offset:49152
	ds_read_b128 v[164:167], v254 offset:50176
	ds_read_b128 v[168:171], v254 offset:51200
	ds_read_b128 v[172:175], v254 offset:52224
	s_add_u32 s64, s64, 0x4000
	s_addc_u32 s65, s65, 0
	s_mov_b32 m0, s41
	ds_read_b128 v[176:179], v163 offset:32768
	ds_read_b128 v[180:183], v163 offset:33792
	ds_read_b128 v[184:187], v163 offset:34816
	ds_read_b128 v[188:191], v163 offset:35840
	ds_read_b128 v[192:195], v163 offset:36864
	ds_read_b128 v[196:199], v163 offset:37888
	ds_read_b128 v[200:203], v163 offset:38912
	ds_read_b128 v[204:207], v163 offset:39936
	global_load_lds_dwordx4 v150, s[64:65]
	s_mov_b32 m0, s42
	s_nop 0
	global_load_lds_dwordx4 v146, s[64:65]
	s_waitcnt vmcnt(8) lgkmcnt(0)
	s_barrier
	v_mfma_f32_16x16x32_bf16 v[124:127], v[128:131], v[176:179], v[124:127]
	v_mfma_f32_16x16x32_bf16 v[120:123], v[136:139], v[176:179], v[120:123]
	v_mfma_f32_16x16x32_bf16 v[108:111], v[128:131], v[184:187], v[108:111]
	v_mfma_f32_16x16x32_bf16 v[104:107], v[136:139], v[184:187], v[104:107]
	v_mfma_f32_16x16x32_bf16 v[92:95], v[128:131], v[192:195], v[92:95]
	v_mfma_f32_16x16x32_bf16 v[88:91], v[136:139], v[192:195], v[88:91]
	v_mfma_f32_16x16x32_bf16 v[76:79], v[128:131], v[200:203], v[76:79]
	v_mfma_f32_16x16x32_bf16 v[72:75], v[136:139], v[200:203], v[72:75]
	v_mfma_f32_16x16x32_bf16 v[124:127], v[132:135], v[180:183], v[124:127]
	v_mfma_f32_16x16x32_bf16 v[120:123], v[140:143], v[180:183], v[120:123]
	v_mfma_f32_16x16x32_bf16 v[108:111], v[132:135], v[188:191], v[108:111]
	v_mfma_f32_16x16x32_bf16 v[104:107], v[140:143], v[188:191], v[104:107]
	v_mfma_f32_16x16x32_bf16 v[92:95], v[132:135], v[196:199], v[92:95]
	v_mfma_f32_16x16x32_bf16 v[88:91], v[140:143], v[196:199], v[88:91]
	v_mfma_f32_16x16x32_bf16 v[76:79], v[132:135], v[204:207], v[76:79]
	v_mfma_f32_16x16x32_bf16 v[72:75], v[140:143], v[204:207], v[72:75]
	v_mfma_f32_16x16x32_bf16 v[116:119], v[156:159], v[176:179], v[116:119]
	v_mfma_f32_16x16x32_bf16 v[112:115], v[168:171], v[176:179], v[112:115]
	v_mfma_f32_16x16x32_bf16 v[100:103], v[156:159], v[184:187], v[100:103]
	v_mfma_f32_16x16x32_bf16 v[96:99], v[168:171], v[184:187], v[96:99]
	v_mfma_f32_16x16x32_bf16 v[84:87], v[156:159], v[192:195], v[84:87]
	v_mfma_f32_16x16x32_bf16 v[80:83], v[168:171], v[192:195], v[80:83]
	v_mfma_f32_16x16x32_bf16 v[68:71], v[156:159], v[200:203], v[68:71]
	v_mfma_f32_16x16x32_bf16 v[64:67], v[168:171], v[200:203], v[64:67]
	v_mfma_f32_16x16x32_bf16 v[116:119], v[164:167], v[180:183], v[116:119]
	v_mfma_f32_16x16x32_bf16 v[112:115], v[172:175], v[180:183], v[112:115]
	v_mfma_f32_16x16x32_bf16 v[100:103], v[164:167], v[188:191], v[100:103]
	v_mfma_f32_16x16x32_bf16 v[96:99], v[172:175], v[188:191], v[96:99]
	v_mfma_f32_16x16x32_bf16 v[84:87], v[164:167], v[196:199], v[84:87]
	v_mfma_f32_16x16x32_bf16 v[80:83], v[172:175], v[196:199], v[80:83]
	v_mfma_f32_16x16x32_bf16 v[68:71], v[164:167], v[204:207], v[68:71]
	v_mfma_f32_16x16x32_bf16 v[64:67], v[172:175], v[204:207], v[64:67]
	s_barrier
; #define PG8_STAGE(bufoff, gbase, voff) do { _Pragma("unroll") for (int _i = 0; _i < 2; ++_i) \
;         __builtin_amdgcn_global_load_lds((const unsigned*)((const char*)(gbase) + (voff)[_i]), (PG8_LAS unsigned*)(lds + (bufoff) + ldsw + _i * 8192), 16, 0, 0); } while (0)
; #define PG8_LDA(dst, b, h) do { _Pragma("unroll") for (int m = 0; m < 4; ++m) _Pragma("unroll") for (int k = 0; k < 2; ++k) dst[m][k] = *(const PG8_LAS bf16x8*)(lds + PG8_SA(b, h) + aoff + m * 2048 + k * 1024); } while (0)
; #define PG8_MMA(ai, bj, At, Bt) do { __builtin_amdgcn_s_setprio(1); _Pragma("unroll") for (int m = 0; m < 4; ++m) _Pragma("unroll") for (int n = 0; n < 2; ++n) _Pragma("unroll") for (int k = 0; k < 2; ++k) \
;         acc[ai][bj][m][n] = __builtin_amdgcn_mfma_f32_16x16x32_bf16(Bt[n][k], At[m][k], acc[ai][bj][m][n], 0, 0, 0); __builtin_amdgcn_s_setprio(0); } while (0)
; #define PG8_WAIT_V(n) asm volatile("s_waitcnt vmcnt(" #n ")" ::: "memory")
; #define PG8_WAIT_L(n) asm volatile("s_waitcnt lgkmcnt(" #n ")" ::: "memory")
; #define PG8_BAR __builtin_amdgcn_s_barrier()
; #define PG8_SCHED __builtin_amdgcn_sched_barrier(0)
; template <class Epi, class Sched, bool ALIGN_EPI = false, bool SP2 = false>
; __device__ __forceinline__ void gemm_phase(PG8_LAS unsigned char* lds, const Gemm g, const Sched& S, const Epi& E) {
;     ...
;             PG8_LDA(At, 1, 1); PG8_STAGE(PG8_SB(1, 0), b3, voffB); PG8_STAGE(PG8_SB(1, 1), b3 + hstep, voffB); PG8_STAGE(PG8_SA(1, 0), a3, voffA);
;             PG8_WAIT_V(8); PG8_WAIT_L(0); PG8_BAR; PG8_MMA(1, 0, At, B0); PG8_MMA(1, 1, At, B1); PG8_BAR; PG8_SCHED;
;     __device__ __forceinline__ void operator()(const f32x4 (&acc)[2][2][4][2], const Unit& u, int wr, int wc, int, int) const {
;     ...
;             for (int m = 0; m < 4; ++m) pq[ai][m] = *(const v4f*)(ssp + (size_t)(row0 + ai * HALF + m * 16) * 16 + 4 * fq);
;         asm volatile("" ::: "memory");
; #pragma unroll
;         for (int ai = 0; ai < 2; ++ai)
; #pragma unroll
;             for (int m = 0; m < 4; ++m) {
;                 const int row = row0 + ai * HALF + m * 16; const float rs = rstd_from_quarter(pq[ai][m], fq * 16 + fr);
	s_add_u32 s64, s62, 0x8000
	s_addc_u32 s65, s63, 0
	s_add_i32 s69, s69, s30
	s_mov_b32 m0, s69
	ds_read_b128 v[176:179], v163 offset:49152
	ds_read_b128 v[180:183], v163 offset:50176
	ds_read_b128 v[184:187], v163 offset:51200
	ds_read_b128 v[188:191], v163 offset:52224
	ds_read_b128 v[192:195], v163 offset:53248
	ds_read_b128 v[196:199], v163 offset:54272
	ds_read_b128 v[200:203], v163 offset:55296
	ds_read_b128 v[204:207], v163 offset:56320
	global_load_lds_dwordx4 v148, s[64:65]
	s_add_i32 m0, s69, 0x2000
	s_add_u32 s62, s62, 0xc000
	s_addc_u32 s63, s63, 0
	s_add_i32 s91, s70, s30
	global_load_lds_dwordx4 v144, s[64:65]
	s_mov_b32 m0, s91
	s_nop 0
	global_load_lds_dwordx4 v148, s[62:63]
	s_add_i32 m0, s91, 0x2000
	s_nop 0
	global_load_lds_dwordx4 v144, s[62:63]
	s_mov_b32 m0, s54
	s_nop 0
	global_load_lds_dwordx4 v150, s[20:21]
	s_mov_b32 m0, s55
	s_nop 0
	global_load_lds_dwordx4 v146, s[20:21]
	s_waitcnt vmcnt(8) lgkmcnt(0)
	s_barrier
	v_mfma_f32_16x16x32_bf16 v[60:63], v[128:131], v[176:179], v[60:63]
	v_mfma_f32_16x16x32_bf16 v[56:59], v[136:139], v[176:179], v[56:59]
	v_mfma_f32_16x16x32_bf16 v[44:47], v[128:131], v[184:187], v[44:47]
	v_mfma_f32_16x16x32_bf16 v[40:43], v[136:139], v[184:187], v[40:43]
	v_mfma_f32_16x16x32_bf16 v[28:31], v[128:131], v[192:195], v[28:31]
	v_mfma_f32_16x16x32_bf16 v[24:27], v[136:139], v[192:195], v[24:27]
	v_mfma_f32_16x16x32_bf16 v[12:15], v[128:131], v[200:203], v[12:15]
	v_mfma_f32_16x16x32_bf16 v[8:11], v[136:139], v[200:203], v[8:11]
	v_mfma_f32_16x16x32_bf16 v[60:63], v[132:135], v[180:183], v[60:63]
	v_mfma_f32_16x16x32_bf16 v[56:59], v[140:143], v[180:183], v[56:59]
	v_mfma_f32_16x16x32_bf16 v[44:47], v[132:135], v[188:191], v[44:47]
	v_mfma_f32_16x16x32_bf16 v[40:43], v[140:143], v[188:191], v[40:43]
	v_mfma_f32_16x16x32_bf16 v[28:31], v[132:135], v[196:199], v[28:31]
	v_mfma_f32_16x16x32_bf16 v[24:27], v[140:143], v[196:199], v[24:27]
	v_mfma_f32_16x16x32_bf16 v[12:15], v[132:135], v[204:207], v[12:15]
	v_mfma_f32_16x16x32_bf16 v[8:11], v[140:143], v[204:207], v[8:11]
	v_mfma_f32_16x16x32_bf16 v[52:55], v[156:159], v[176:179], v[52:55]
	v_mfma_f32_16x16x32_bf16 v[48:51], v[168:171], v[176:179], v[48:51]
	v_mfma_f32_16x16x32_bf16 v[36:39], v[156:159], v[184:187], v[36:39]
	v_mfma_f32_16x16x32_bf16 v[32:35], v[168:171], v[184:187], v[32:35]
	v_mfma_f32_16x16x32_bf16 v[20:23], v[156:159], v[192:195], v[20:23]
	v_mfma_f32_16x16x32_bf16 v[16:19], v[168:171], v[192:195], v[16:19]
	v_mfma_f32_16x16x32_bf16 v[4:7], v[156:159], v[200:203], v[4:7]
	v_mfma_f32_16x16x32_bf16 v[0:3], v[168:171], v[200:203], v[0:3]
	v_mfma_f32_16x16x32_bf16 v[52:55], v[164:167], v[180:183], v[52:55]
	v_mfma_f32_16x16x32_bf16 v[48:51], v[172:175], v[180:183], v[48:51]
	v_mfma_f32_16x16x32_bf16 v[36:39], v[164:167], v[188:191], v[36:39]
	v_mfma_f32_16x16x32_bf16 v[32:35], v[172:175], v[188:191], v[32:35]
	v_mfma_f32_16x16x32_bf16 v[20:23], v[164:167], v[196:199], v[20:23]
	v_mfma_f32_16x16x32_bf16 v[16:19], v[172:175], v[196:199], v[16:19]
	v_mfma_f32_16x16x32_bf16 v[4:7], v[164:167], v[204:207], v[4:7]
	v_mfma_f32_16x16x32_bf16 v[0:3], v[172:175], v[204:207], v[0:3]
	s_barrier
	s_add_i32 s68, s68, 2
	s_add_u32 s18, s18, 0x10000
	s_addc_u32 s19, s19, 0
	s_add_u32 s66, s66, 0x10000
	s_addc_u32 s67, s67, 0
	s_cmp_gt_u32 s68, 13
	s_cbranch_scc0 .LBB0_1356
	s_and_b64 vcc, exec, s[6:7]
	s_cbranch_vccz .LBB0_1359
	s_barrier
.LBB0_1359:
	s_lshl_b32 s91, s10, 8
	s_add_i32 s91, s91, s77
	v_and_or_b32 v232, v230, 15, s91
	v_bfe_u32 v233, v230, 4, 2
	v_lshlrev_b32_e32 v232, 6, v232
	v_lshl_add_u32 v232, v233, 4, v232
	v_add_u32_e32 v233, 0x2000, v232
	s_lshl_b32 s9, s16, 8
	v_mov_b32_e32 v142, v230
	s_add_i32 s9, s9, s52
	s_mov_b32 s16, 0x358637bd
	v_and_or_b32 v136, v142, 15, s9
	v_bfe_u32 v143, v142, 4, 2
	v_or_b32_e32 v132, 16, v136
	v_lshlrev_b32_e32 v220, 4, v143
	v_ashrrev_i32_e32 v137, 31, v136
	v_ashrrev_i32_e32 v133, 31, v132
	v_lshl_add_u64 v[138:139], s[4:5], 0, v[220:221]
	v_lshlrev_b64 v[128:129], 6, v[136:137]
	v_lshlrev_b64 v[132:133], 6, v[132:133]
	v_lshl_add_u64 v[140:141], v[138:139], 0, v[128:129]
	v_lshl_add_u64 v[132:133], v[138:139], 0, v[132:133]
	v_mov_b64_e32 v[128:129], v[208:209]
	v_mov_b64_e32 v[130:131], v[210:211]
	global_load_dwordx4 v[208:211], v232, s[92:93]
	v_lshlrev_b32_e32 v137, 2, v142
	v_mov_b64_e32 v[132:133], v[212:213]
	v_mov_b64_e32 v[134:135], v[214:215]
	global_load_dwordx4 v[212:215], v232, s[92:93] offset:1024
	v_or_b32_e32 v142, 32, v136
	v_or_b32_e32 v160, 48, v136
	v_add_u32_e32 v158, 0x80, v136
	v_lshl_or_b32 v166, v143, 3, s56
	v_lshlrev_b32_e32 v136, 6, v136
	v_ashrrev_i32_e32 v143, 31, v142
	v_bitop3_b32 v165, v137, 64, v244 bitop3:0x6c
	v_bitop3_b32 v164, v137, s90, v244 bitop3:0x6c
	v_ashrrev_i32_e32 v161, 31, v160
	v_and_or_b32 v167, v136, s84, v166
	v_lshlrev_b64 v[136:137], 6, v[142:143]
	v_lshlrev_b64 v[142:143], 6, v[160:161]
	v_lshl_add_u64 v[136:137], v[138:139], 0, v[136:137]
	v_lshl_add_u64 v[142:143], v[138:139], 0, v[142:143]
	v_mov_b64_e32 v[168:169], v[216:217]
	v_mov_b64_e32 v[170:171], v[218:219]
	global_load_dwordx4 v[216:219], v232, s[92:93] offset:2048
	v_mov_b64_e32 v[172:173], v[222:223]
	v_mov_b64_e32 v[174:175], v[224:225]
	global_load_dwordx4 v[222:225], v232, s[92:93] offset:3072
	v_ashrrev_i32_e32 v159, 31, v158
	v_lshlrev_b64 v[160:161], 6, v[158:159]
	v_lshl_add_u64 v[138:139], v[138:139], 0, v[160:161]
	s_lshl_b32 s11, s17, 7
	v_mov_b64_e32 v[156:157], s[16:17]
	s_or_b32 s11, s11, s53
	s_ashr_i32 s16, s11, 6
	s_ashr_i32 s17, s16, 31
	s_ashr_i32 s9, s9, 8
	s_lshl_b64 s[16:17], s[16:17], 15
	s_add_u32 s16, s50, s16
	v_lshlrev_b32_e32 v220, 1, v167
	s_addc_u32 s17, s51, s17
	v_lshl_add_u64 v[176:177], s[16:17], 0, v[220:221]
	v_mov_b32_e32 v160, v129
	v_mov_b32_e32 v161, v130
	v_mov_b32_e32 v129, v131
	v_mov_b32_e32 v130, v133
	v_mov_b32_e32 v131, v134
	v_mov_b32_e32 v133, v135
	v_pk_add_f32 v[128:129], v[160:161], v[128:129]
	v_pk_add_f32 v[130:131], v[130:131], v[132:133]
	v_mov_b32_e32 v133, v128
	v_mov_b32_e32 v132, v130
	v_mov_b32_e32 v128, v131
	v_pk_add_f32 v[128:129], v[132:133], v[128:129]
	ds_bpermute_b32 v131, v165, v129
	ds_bpermute_b32 v130, v165, v128
	v_add_co_u32_e32 v160, vcc, s80, v140
	s_waitcnt lgkmcnt(0)
; __device__ __forceinline__ v4u pack8(const float* x) { v4u o; o.x = pk2(x[0], x[1]); o.y = pk2(x[2], x[3]); o.z = pk2(x[4], x[5]); o.w = pk2(x[6], x[7]); return o; }
; __device__ __forceinline__ size_t tl(int row, int col, int K) { return (size_t)(row >> 8) * ((size_t)256 * K) + (size_t)(col >> 6) * (256 * 64) + (size_t)((row & 255) * 64 + (col & 63)); }
;     __device__ __forceinline__ void operator()(const f32x4 (&acc)[2][2][4][2], const Unit& u, int wr, int wc, int, int) const {
;     ...
;             for (int m = 0; m < 4; ++m) pq[ai][m] = *(const v4f*)(ssp + (size_t)(row0 + ai * HALF + m * 16) * 16 + 4 * fq);
;         asm volatile("" ::: "memory");
; #pragma unroll
;         for (int ai = 0; ai < 2; ++ai)
; #pragma unroll
;             for (int m = 0; m < 4; ++m) {
;                 const int row = row0 + ai * HALF + m * 16; const float rs = rstd_from_quarter(pq[ai][m], fq * 16 + fr);
;                 float h[8];
; #pragma unroll
;                 for (int n = 0; n < 2; ++n) { const f32x4 g = acc[ai][0][m][n] * rs, uu = acc[ai][1][m][n] * rs; const f32x4 hv = (g * sigmoid4(g)) * uu;
;                     h[n * 4 + 0] = hv[0]; h[n * 4 + 1] = hv[1]; h[n * 4 + 2] = hv[2]; h[n * 4 + 3] = hv[3]; }
;                 __builtin_nontemporal_store(pack8(h), (u32x4*)(O + tl(row, col0, FF)));
	v_pk_add_f32 v[178:179], v[128:129], v[130:131]
	ds_bpermute_b32 v181, v164, v179
	ds_bpermute_b32 v180, v164, v178
	v_addc_co_u32_e32 v161, vcc, 0, v141, vcc
	v_mov_b64_e32 v[140:141], v[226:227]
	v_mov_b64_e32 v[142:143], v[228:229]
	global_load_dwordx4 v[226:229], v233, s[92:93]
	s_nop 0
	v_mov_b64_e32 v[136:137], v[240:241]
	v_mov_b64_e32 v[138:139], v[242:243]
	global_load_dwordx4 v[240:243], v233, s[92:93] offset:1024
	v_mov_b64_e32 v[132:133], v[246:247]
	v_mov_b64_e32 v[134:135], v[248:249]
	global_load_dwordx4 v[246:249], v233, s[92:93] offset:2048
	v_mov_b64_e32 v[128:129], v[250:251]
	v_mov_b64_e32 v[130:131], v[252:253]
	global_load_dwordx4 v[250:253], v233, s[92:93] offset:3072
	s_waitcnt lgkmcnt(0)
	v_pk_add_f32 v[160:161], v[178:179], v[180:181]
	s_nop 0
	v_pk_fma_f32 v[178:179], v[160:161], s[74:75], v[156:157] op_sel_hi:[1,0,0]
	v_mad_i64_i32 v[160:161], s[18:19], s9, v245, v[176:177]
	v_mul_f32_e32 v159, 0x4b800000, v179
	v_cmp_gt_f32_e32 vcc, s25, v179
	v_mul_f32_e32 v167, 0x4b800000, v178
	s_nop 0
	v_cndmask_b32_e32 v159, v179, v159, vcc
	v_rsq_f32_e32 v159, v159
	s_nop 0
	v_mul_f32_e32 v176, 0x45800000, v159
	v_cndmask_b32_e32 v176, v159, v176, vcc
	v_pk_mul_f32 v[120:121], v[120:121], v[176:177] op_sel_hi:[1,0]
	v_pk_mul_f32 v[122:123], v[122:123], v[176:177] op_sel_hi:[1,0]
	v_pk_mul_f32 v[184:185], v[120:121], s[38:39] op_sel_hi:[1,0]
	v_pk_mul_f32 v[182:183], v[122:123], s[38:39] op_sel_hi:[1,0]
	v_exp_f32_e32 v184, v184
	v_exp_f32_e32 v182, v182
	v_exp_f32_e32 v183, v183
	v_exp_f32_e32 v185, v185
	v_pk_mul_f32 v[124:125], v[124:125], v[176:177] op_sel_hi:[1,0]
	v_pk_mul_f32 v[126:127], v[126:127], v[176:177] op_sel_hi:[1,0]
	v_pk_mul_f32 v[180:181], v[124:125], s[38:39] op_sel_hi:[1,0]
	v_pk_add_f32 v[182:183], v[182:183], 1.0 op_sel_hi:[1,0]
	v_pk_add_f32 v[184:185], v[184:185], 1.0 op_sel_hi:[1,0]
	v_exp_f32_e32 v180, v180
	v_exp_f32_e32 v181, v181
	v_rcp_f32_e32 v184, v184
	v_rcp_f32_e32 v185, v185
	v_rcp_f32_e32 v182, v182
	v_rcp_f32_e32 v183, v183
	v_pk_mul_f32 v[116:117], v[116:117], v[176:177] op_sel_hi:[1,0]
	v_pk_mul_f32 v[118:119], v[118:119], v[176:177] op_sel_hi:[1,0]
	v_pk_mul_f32 v[112:113], v[112:113], v[176:177] op_sel_hi:[1,0]
	v_pk_mul_f32 v[114:115], v[114:115], v[176:177] op_sel_hi:[1,0]
	v_pk_mul_f32 v[176:177], v[126:127], s[38:39] op_sel_hi:[1,0]
	v_pk_add_f32 v[180:181], v[180:181], 1.0 op_sel_hi:[1,0]
	v_exp_f32_e32 v176, v176
	v_exp_f32_e32 v177, v177
	v_pk_mul_f32 v[120:121], v[120:121], v[184:185]
	v_pk_mul_f32 v[122:123], v[122:123], v[182:183]
	v_cmp_gt_f32_e32 vcc, s25, v178
	v_rcp_f32_e32 v180, v180
	v_rcp_f32_e32 v181, v181
	v_pk_mul_f32 v[122:123], v[114:115], v[122:123]
	v_pk_mul_f32 v[114:115], v[112:113], v[120:121]
	v_cndmask_b32_e32 v112, v178, v167, vcc
	v_pk_add_f32 v[176:177], v[176:177], 1.0 op_sel_hi:[1,0]
	v_rsq_f32_e32 v120, v112
	v_rcp_f32_e32 v176, v176
	v_rcp_f32_e32 v177, v177
	v_pk_mul_f32 v[124:125], v[124:125], v[180:181]
	v_cvt_pk_bf16_f32 v114, v114, v115
	v_pk_mul_f32 v[116:117], v[116:117], v[124:125]
	v_mul_f32_e32 v115, 0x45800000, v120
	v_pk_mul_f32 v[126:127], v[126:127], v[176:177]
	v_cvt_pk_bf16_f32 v112, v116, v117
	v_cndmask_b32_e32 v116, v120, v115, vcc
	v_pk_mul_f32 v[118:119], v[118:119], v[126:127]
	v_pk_mul_f32 v[108:109], v[108:109], v[116:117] op_sel_hi:[1,0]
	v_pk_mul_f32 v[110:111], v[110:111], v[116:117] op_sel_hi:[1,0]
	v_cvt_pk_bf16_f32 v113, v118, v119
	v_pk_mul_f32 v[118:119], v[110:111], s[38:39] op_sel_hi:[1,0]
	v_pk_mul_f32 v[120:121], v[108:109], s[38:39] op_sel_hi:[1,0]
	v_exp_f32_e32 v118, v118
	v_exp_f32_e32 v120, v120
	v_exp_f32_e32 v119, v119
	v_exp_f32_e32 v121, v121
	v_cvt_pk_bf16_f32 v115, v122, v123
	global_store_dwordx4 v[160:161], v[112:115], off nt
	v_pk_mul_f32 v[100:101], v[100:101], v[116:117] op_sel_hi:[1,0]
	v_pk_mul_f32 v[102:103], v[102:103], v[116:117] op_sel_hi:[1,0]
	v_pk_add_f32 v[112:113], v[118:119], 1.0 op_sel_hi:[1,0]
	v_pk_add_f32 v[114:115], v[120:121], 1.0 op_sel_hi:[1,0]
	v_rcp_f32_e32 v112, v112
	v_rcp_f32_e32 v114, v114
	v_rcp_f32_e32 v115, v115
	v_rcp_f32_e32 v113, v113
	v_pk_mul_f32 v[104:105], v[104:105], v[116:117] op_sel_hi:[1,0]
	v_pk_mul_f32 v[106:107], v[106:107], v[116:117] op_sel_hi:[1,0]
	v_pk_mul_f32 v[108:109], v[108:109], v[114:115]
	v_pk_mul_f32 v[110:111], v[110:111], v[112:113]
	v_mov_b32_e32 v112, v169
	v_mov_b32_e32 v113, v170
	v_mov_b32_e32 v169, v171
	v_mov_b32_e32 v114, v173
	v_mov_b32_e32 v115, v174
	v_mov_b32_e32 v173, v175
	v_pk_add_f32 v[112:113], v[112:113], v[168:169]
	v_pk_add_f32 v[114:115], v[114:115], v[172:173]
	v_pk_mul_f32 v[96:97], v[96:97], v[116:117] op_sel_hi:[1,0]
	v_pk_mul_f32 v[98:99], v[98:99], v[116:117] op_sel_hi:[1,0]
	v_mov_b32_e32 v116, v114
	v_mov_b32_e32 v117, v112
	v_mov_b32_e32 v112, v115
	v_pk_add_f32 v[112:113], v[116:117], v[112:113]
	v_pk_mul_f32 v[102:103], v[102:103], v[110:111]
	v_pk_mul_f32 v[100:101], v[100:101], v[108:109]
	v_pk_mul_f32 v[108:109], v[106:107], s[38:39] op_sel_hi:[1,0]
	v_pk_mul_f32 v[110:111], v[104:105], s[38:39] op_sel_hi:[1,0]
	ds_bpermute_b32 v115, v165, v113
	ds_bpermute_b32 v114, v165, v112
	v_exp_f32_e32 v110, v110
	v_exp_f32_e32 v108, v108
	v_exp_f32_e32 v109, v109
	v_exp_f32_e32 v111, v111
	s_waitcnt lgkmcnt(0)
	v_pk_add_f32 v[112:113], v[112:113], v[114:115]
	ds_bpermute_b32 v115, v164, v113
	v_pk_add_f32 v[108:109], v[108:109], 1.0 op_sel_hi:[1,0]
	v_pk_add_f32 v[110:111], v[110:111], 1.0 op_sel_hi:[1,0]
	v_rcp_f32_e32 v108, v108
	v_rcp_f32_e32 v110, v110
	v_rcp_f32_e32 v111, v111
	v_rcp_f32_e32 v109, v109
	ds_bpermute_b32 v114, v164, v112
	v_pk_mul_f32 v[104:105], v[104:105], v[110:111]
	v_pk_mul_f32 v[106:107], v[106:107], v[108:109]
	s_nop 0
	v_pk_mul_f32 v[106:107], v[98:99], v[106:107]
	v_pk_mul_f32 v[98:99], v[96:97], v[104:105]
	s_waitcnt lgkmcnt(0)
; __device__ __forceinline__ v4u pack8(const float* x) { v4u o; o.x = pk2(x[0], x[1]); o.y = pk2(x[2], x[3]); o.z = pk2(x[4], x[5]); o.w = pk2(x[6], x[7]); return o; }
; __device__ __forceinline__ size_t tl(int row, int col, int K) { return (size_t)(row >> 8) * ((size_t)256 * K) + (size_t)(col >> 6) * (256 * 64) + (size_t)((row & 255) * 64 + (col & 63)); }
;     __device__ __forceinline__ void operator()(const f32x4 (&acc)[2][2][4][2], const Unit& u, int wr, int wc, int, int) const {
;     ...
;                 const int row = row0 + ai * HALF + m * 16; const float rs = rstd_from_quarter(pq[ai][m], fq * 16 + fr);
;                 float h[8];
; #pragma unroll
;                 for (int n = 0; n < 2; ++n) { const f32x4 g = acc[ai][0][m][n] * rs, uu = acc[ai][1][m][n] * rs; const f32x4 hv = (g * sigmoid4(g)) * uu;
;                     h[n * 4 + 0] = hv[0]; h[n * 4 + 1] = hv[1]; h[n * 4 + 2] = hv[2]; h[n * 4 + 3] = hv[3]; }
;                 __builtin_nontemporal_store(pack8(h), (u32x4*)(O + tl(row, col0, FF)));
	v_pk_add_f32 v[96:97], v[112:113], v[114:115]
	v_cvt_pk_bf16_f32 v98, v98, v99
	v_pk_fma_f32 v[104:105], v[96:97], s[74:75], v[156:157] op_sel_hi:[1,0,0]
	v_cvt_pk_bf16_f32 v97, v102, v103
	v_mul_f32_e32 v96, 0x4b800000, v105
	v_cmp_gt_f32_e32 vcc, s25, v105
	s_nop 1
	v_cndmask_b32_e32 v96, v105, v96, vcc
	v_rsq_f32_e32 v105, v96
	v_cvt_pk_bf16_f32 v96, v100, v101
	v_mul_f32_e32 v99, 0x45800000, v105
	v_cndmask_b32_e32 v100, v105, v99, vcc
	v_pk_mul_f32 v[92:93], v[92:93], v[100:101] op_sel_hi:[1,0]
	v_pk_mul_f32 v[94:95], v[94:95], v[100:101] op_sel_hi:[1,0]
	v_pk_mul_f32 v[108:109], v[92:93], s[38:39] op_sel_hi:[1,0]
	v_pk_mul_f32 v[102:103], v[94:95], s[38:39] op_sel_hi:[1,0]
	v_exp_f32_e32 v108, v108
	v_exp_f32_e32 v102, v102
	v_exp_f32_e32 v103, v103
	v_exp_f32_e32 v109, v109
	v_cvt_pk_bf16_f32 v99, v106, v107
	global_store_dwordx4 v[160:161], v[96:99], off offset:2048 nt
	v_pk_mul_f32 v[88:89], v[88:89], v[100:101] op_sel_hi:[1,0]
	v_pk_mul_f32 v[90:91], v[90:91], v[100:101] op_sel_hi:[1,0]
	v_pk_add_f32 v[96:97], v[102:103], 1.0 op_sel_hi:[1,0]
	v_pk_add_f32 v[98:99], v[108:109], 1.0 op_sel_hi:[1,0]
	v_rcp_f32_e32 v96, v96
	v_rcp_f32_e32 v98, v98
	v_rcp_f32_e32 v99, v99
	v_rcp_f32_e32 v97, v97
	v_pk_mul_f32 v[84:85], v[84:85], v[100:101] op_sel_hi:[1,0]
	v_pk_mul_f32 v[86:87], v[86:87], v[100:101] op_sel_hi:[1,0]
	v_pk_mul_f32 v[92:93], v[92:93], v[98:99]
	v_pk_mul_f32 v[94:95], v[94:95], v[96:97]
	v_pk_mul_f32 v[96:97], v[90:91], s[38:39] op_sel_hi:[1,0]
	v_pk_mul_f32 v[98:99], v[88:89], s[38:39] op_sel_hi:[1,0]
	v_exp_f32_e32 v96, v96
	v_exp_f32_e32 v98, v98
	v_exp_f32_e32 v97, v97
	v_exp_f32_e32 v99, v99
	v_pk_mul_f32 v[86:87], v[86:87], v[94:95]
	v_pk_mul_f32 v[84:85], v[84:85], v[92:93]
	v_pk_add_f32 v[92:93], v[96:97], 1.0 op_sel_hi:[1,0]
	v_pk_add_f32 v[94:95], v[98:99], 1.0 op_sel_hi:[1,0]
	v_rcp_f32_e32 v92, v92
	v_rcp_f32_e32 v94, v94
	v_rcp_f32_e32 v95, v95
	v_rcp_f32_e32 v93, v93
	v_pk_mul_f32 v[80:81], v[80:81], v[100:101] op_sel_hi:[1,0]
	v_pk_mul_f32 v[82:83], v[82:83], v[100:101] op_sel_hi:[1,0]
	v_pk_mul_f32 v[88:89], v[88:89], v[94:95]
	v_pk_mul_f32 v[90:91], v[90:91], v[92:93]
	v_cmp_gt_f32_e32 vcc, s25, v104
	v_pk_mul_f32 v[90:91], v[82:83], v[90:91]
	v_pk_mul_f32 v[82:83], v[80:81], v[88:89]
	v_mul_f32_e32 v81, 0x4b800000, v104
	v_cndmask_b32_e32 v81, v104, v81, vcc
	v_cvt_pk_bf16_f32 v80, v84, v85
	v_rsq_f32_e32 v84, v81
	v_cvt_pk_bf16_f32 v81, v86, v87
	v_cvt_pk_bf16_f32 v82, v82, v83
	v_cvt_pk_bf16_f32 v83, v90, v91
	v_mul_f32_e32 v85, 0x45800000, v84
	v_cndmask_b32_e32 v84, v84, v85, vcc
	v_pk_mul_f32 v[76:77], v[76:77], v[84:85] op_sel_hi:[1,0]
	v_pk_mul_f32 v[78:79], v[78:79], v[84:85] op_sel_hi:[1,0]
	v_pk_mul_f32 v[88:89], v[76:77], s[38:39] op_sel_hi:[1,0]
	v_pk_mul_f32 v[86:87], v[78:79], s[38:39] op_sel_hi:[1,0]
	v_exp_f32_e32 v88, v88
	v_exp_f32_e32 v89, v89
	v_exp_f32_e32 v86, v86
	v_exp_f32_e32 v87, v87
	v_add_co_u32_e32 v90, vcc, s85, v160
	v_pk_mul_f32 v[72:73], v[72:73], v[84:85] op_sel_hi:[1,0]
	s_nop 0
	v_addc_co_u32_e32 v91, vcc, 0, v161, vcc
	global_store_dwordx4 v[90:91], v[80:83], off nt
	v_pk_mul_f32 v[74:75], v[74:75], v[84:85] op_sel_hi:[1,0]
	v_pk_mul_f32 v[68:69], v[68:69], v[84:85] op_sel_hi:[1,0]
	v_pk_add_f32 v[80:81], v[86:87], 1.0 op_sel_hi:[1,0]
	v_pk_add_f32 v[82:83], v[88:89], 1.0 op_sel_hi:[1,0]
	v_rcp_f32_e32 v80, v80
	v_rcp_f32_e32 v82, v82
	v_rcp_f32_e32 v83, v83
	v_rcp_f32_e32 v81, v81
	v_pk_mul_f32 v[70:71], v[70:71], v[84:85] op_sel_hi:[1,0]
	v_pk_mul_f32 v[64:65], v[64:65], v[84:85] op_sel_hi:[1,0]
	v_pk_mul_f32 v[76:77], v[76:77], v[82:83]
	v_pk_mul_f32 v[78:79], v[78:79], v[80:81]
	v_pk_mul_f32 v[80:81], v[74:75], s[38:39] op_sel_hi:[1,0]
	v_pk_mul_f32 v[82:83], v[72:73], s[38:39] op_sel_hi:[1,0]
	v_exp_f32_e32 v80, v80
	v_exp_f32_e32 v82, v82
	v_exp_f32_e32 v81, v81
	v_exp_f32_e32 v83, v83
	v_pk_mul_f32 v[70:71], v[70:71], v[78:79]
	v_pk_mul_f32 v[68:69], v[68:69], v[76:77]
	v_pk_add_f32 v[76:77], v[80:81], 1.0 op_sel_hi:[1,0]
	v_pk_add_f32 v[78:79], v[82:83], 1.0 op_sel_hi:[1,0]
	v_rcp_f32_e32 v76, v76
	v_rcp_f32_e32 v78, v78
	v_rcp_f32_e32 v79, v79
	v_rcp_f32_e32 v77, v77
	v_pk_mul_f32 v[66:67], v[66:67], v[84:85] op_sel_hi:[1,0]
	v_pk_mul_f32 v[72:73], v[72:73], v[78:79]
	v_pk_mul_f32 v[74:75], v[74:75], v[76:77]
	s_nop 0
	v_pk_mul_f32 v[74:75], v[66:67], v[74:75]
	v_pk_mul_f32 v[66:67], v[64:65], v[72:73]
	v_mov_b32_e32 v64, v141
	v_mov_b32_e32 v65, v142
	v_mov_b32_e32 v141, v143
	v_mov_b32_e32 v72, v137
	v_mov_b32_e32 v73, v138
	v_mov_b32_e32 v137, v139
	v_pk_add_f32 v[64:65], v[64:65], v[140:141]
	v_pk_add_f32 v[72:73], v[72:73], v[136:137]
	v_mov_b32_e32 v77, v64
	v_mov_b32_e32 v76, v72
	v_mov_b32_e32 v64, v73
	v_pk_add_f32 v[72:73], v[76:77], v[64:65]
	ds_bpermute_b32 v77, v165, v73
	ds_bpermute_b32 v76, v165, v72
	v_cvt_pk_bf16_f32 v64, v68, v69
	v_cvt_pk_bf16_f32 v65, v70, v71
	v_cvt_pk_bf16_f32 v66, v66, v67
	v_cvt_pk_bf16_f32 v67, v74, v75
	s_waitcnt lgkmcnt(0)
	v_pk_add_f32 v[68:69], v[72:73], v[76:77]
	ds_bpermute_b32 v71, v164, v69
	ds_bpermute_b32 v70, v164, v68
	global_store_dwordx4 v[90:91], v[64:67], off offset:2048 nt
	s_nop 1
	v_lshlrev_b32_e32 v64, 6, v158
	v_and_or_b32 v72, v64, s84, v166
	s_waitcnt lgkmcnt(0)
; __device__ __forceinline__ v4u pack8(const float* x) { v4u o; o.x = pk2(x[0], x[1]); o.y = pk2(x[2], x[3]); o.z = pk2(x[4], x[5]); o.w = pk2(x[6], x[7]); return o; }
; __device__ __forceinline__ size_t tl(int row, int col, int K) { return (size_t)(row >> 8) * ((size_t)256 * K) + (size_t)(col >> 6) * (256 * 64) + (size_t)((row & 255) * 64 + (col & 63)); }
;     __device__ __forceinline__ void operator()(const f32x4 (&acc)[2][2][4][2], const Unit& u, int wr, int wc, int, int) const {
;     ...
;                 const int row = row0 + ai * HALF + m * 16; const float rs = rstd_from_quarter(pq[ai][m], fq * 16 + fr);
;                 float h[8];
; #pragma unroll
;                 for (int n = 0; n < 2; ++n) { const f32x4 g = acc[ai][0][m][n] * rs, uu = acc[ai][1][m][n] * rs; const f32x4 hv = (g * sigmoid4(g)) * uu;
;                     h[n * 4 + 0] = hv[0]; h[n * 4 + 1] = hv[1]; h[n * 4 + 2] = hv[2]; h[n * 4 + 3] = hv[3]; }
;                 __builtin_nontemporal_store(pack8(h), (u32x4*)(O + tl(row, col0, FF)));
	v_pk_add_f32 v[64:65], v[68:69], v[70:71]
	v_lshlrev_b32_e32 v220, 1, v72
	v_pk_fma_f32 v[64:65], v[64:65], s[74:75], v[156:157] op_sel_hi:[1,0,0]
	v_lshrrev_b32_e32 v66, 8, v158
	v_mul_f32_e32 v67, 0x4b800000, v65
	v_cmp_gt_f32_e32 vcc, s25, v65
	s_nop 1
	v_cndmask_b32_e32 v65, v65, v67, vcc
	v_rsq_f32_e32 v65, v65
	v_mul_hi_i32_i24_e32 v67, 0x160000, v66
	v_mul_i32_i24_e32 v66, 0x160000, v66
	v_mul_f32_e32 v68, 0x45800000, v65
	v_cndmask_b32_e32 v68, v65, v68, vcc
	v_pk_mul_f32 v[70:71], v[60:61], v[68:69] op_sel_hi:[1,0]
	v_pk_mul_f32 v[62:63], v[62:63], v[68:69] op_sel_hi:[1,0]
	v_pk_mul_f32 v[72:73], v[70:71], s[38:39] op_sel_hi:[1,0]
	v_pk_mul_f32 v[60:61], v[62:63], s[38:39] op_sel_hi:[1,0]
	v_exp_f32_e32 v72, v72
	v_exp_f32_e32 v74, v60
	v_exp_f32_e32 v75, v61
	v_exp_f32_e32 v73, v73
	v_lshl_add_u64 v[60:61], s[16:17], 0, v[220:221]
	v_lshl_add_u64 v[60:61], v[60:61], 0, v[66:67]
	v_pk_add_f32 v[66:67], v[74:75], 1.0 op_sel_hi:[1,0]
	v_pk_add_f32 v[72:73], v[72:73], 1.0 op_sel_hi:[1,0]
	v_rcp_f32_e32 v66, v66
	v_rcp_f32_e32 v72, v72
	v_rcp_f32_e32 v73, v73
	v_rcp_f32_e32 v67, v67
	v_pk_mul_f32 v[56:57], v[56:57], v[68:69] op_sel_hi:[1,0]
	v_pk_mul_f32 v[58:59], v[58:59], v[68:69] op_sel_hi:[1,0]
	v_pk_mul_f32 v[70:71], v[70:71], v[72:73]
	v_pk_mul_f32 v[62:63], v[62:63], v[66:67]
	v_pk_mul_f32 v[66:67], v[58:59], s[38:39] op_sel_hi:[1,0]
	v_pk_mul_f32 v[72:73], v[56:57], s[38:39] op_sel_hi:[1,0]
	v_exp_f32_e32 v66, v66
	v_exp_f32_e32 v72, v72
	v_exp_f32_e32 v67, v67
	v_exp_f32_e32 v73, v73
	v_pk_mul_f32 v[54:55], v[54:55], v[68:69] op_sel_hi:[1,0]
	v_pk_mul_f32 v[48:49], v[48:49], v[68:69] op_sel_hi:[1,0]
	v_pk_mul_f32 v[54:55], v[54:55], v[62:63]
	v_pk_add_f32 v[62:63], v[66:67], 1.0 op_sel_hi:[1,0]
	v_pk_add_f32 v[66:67], v[72:73], 1.0 op_sel_hi:[1,0]
	v_rcp_f32_e32 v62, v62
	v_rcp_f32_e32 v66, v66
	v_rcp_f32_e32 v67, v67
	v_rcp_f32_e32 v63, v63
	v_pk_mul_f32 v[50:51], v[50:51], v[68:69] op_sel_hi:[1,0]
	v_cmp_gt_f32_e32 vcc, s25, v64
	v_pk_mul_f32 v[56:57], v[56:57], v[66:67]
	v_pk_mul_f32 v[58:59], v[58:59], v[62:63]
	v_pk_mul_f32 v[52:53], v[52:53], v[68:69] op_sel_hi:[1,0]
	v_pk_mul_f32 v[58:59], v[50:51], v[58:59]
	v_pk_mul_f32 v[50:51], v[48:49], v[56:57]
	v_mul_f32_e32 v48, 0x4b800000, v64
	v_cndmask_b32_e32 v48, v64, v48, vcc
	v_rsq_f32_e32 v56, v48
	v_pk_mul_f32 v[52:53], v[52:53], v[70:71]
	v_cvt_pk_bf16_f32 v50, v50, v51
	v_cvt_pk_bf16_f32 v48, v52, v53
	v_mul_f32_e32 v51, 0x45800000, v56
	v_cndmask_b32_e32 v52, v56, v51, vcc
	v_pk_mul_f32 v[44:45], v[44:45], v[52:53] op_sel_hi:[1,0]
	v_pk_mul_f32 v[46:47], v[46:47], v[52:53] op_sel_hi:[1,0]
	v_cvt_pk_bf16_f32 v49, v54, v55
	v_pk_mul_f32 v[54:55], v[46:47], s[38:39] op_sel_hi:[1,0]
	v_pk_mul_f32 v[56:57], v[44:45], s[38:39] op_sel_hi:[1,0]
	v_exp_f32_e32 v54, v54
	v_exp_f32_e32 v56, v56
	v_exp_f32_e32 v55, v55
	v_exp_f32_e32 v57, v57
	v_cvt_pk_bf16_f32 v51, v58, v59
	global_store_dwordx4 v[60:61], v[48:51], off nt
	v_pk_mul_f32 v[36:37], v[36:37], v[52:53] op_sel_hi:[1,0]
	v_pk_mul_f32 v[38:39], v[38:39], v[52:53] op_sel_hi:[1,0]
	v_pk_add_f32 v[48:49], v[54:55], 1.0 op_sel_hi:[1,0]
	v_pk_add_f32 v[50:51], v[56:57], 1.0 op_sel_hi:[1,0]
	v_rcp_f32_e32 v48, v48
	v_rcp_f32_e32 v50, v50
	v_rcp_f32_e32 v51, v51
	v_rcp_f32_e32 v49, v49
	v_pk_mul_f32 v[40:41], v[40:41], v[52:53] op_sel_hi:[1,0]
	v_pk_mul_f32 v[42:43], v[42:43], v[52:53] op_sel_hi:[1,0]
	v_pk_mul_f32 v[44:45], v[44:45], v[50:51]
	v_pk_mul_f32 v[46:47], v[46:47], v[48:49]
	v_mov_b32_e32 v48, v133
	v_mov_b32_e32 v49, v134
	v_mov_b32_e32 v133, v135
	v_mov_b32_e32 v50, v129
	v_mov_b32_e32 v51, v130
	v_mov_b32_e32 v129, v131
	v_pk_add_f32 v[48:49], v[48:49], v[132:133]
	v_pk_add_f32 v[50:51], v[50:51], v[128:129]
	v_pk_mul_f32 v[32:33], v[32:33], v[52:53] op_sel_hi:[1,0]
	v_pk_mul_f32 v[34:35], v[34:35], v[52:53] op_sel_hi:[1,0]
	v_mov_b32_e32 v52, v50
	v_mov_b32_e32 v53, v48
	v_mov_b32_e32 v48, v51
	v_pk_add_f32 v[48:49], v[52:53], v[48:49]
	v_pk_mul_f32 v[38:39], v[38:39], v[46:47]
	v_pk_mul_f32 v[36:37], v[36:37], v[44:45]
	v_pk_mul_f32 v[44:45], v[42:43], s[38:39] op_sel_hi:[1,0]
	v_pk_mul_f32 v[46:47], v[40:41], s[38:39] op_sel_hi:[1,0]
	ds_bpermute_b32 v51, v165, v49
	ds_bpermute_b32 v50, v165, v48
	v_exp_f32_e32 v46, v46
	v_exp_f32_e32 v44, v44
	v_exp_f32_e32 v45, v45
	v_exp_f32_e32 v47, v47
	s_waitcnt lgkmcnt(0)
	v_pk_add_f32 v[48:49], v[48:49], v[50:51]
	ds_bpermute_b32 v51, v164, v49
	v_pk_add_f32 v[44:45], v[44:45], 1.0 op_sel_hi:[1,0]
	v_pk_add_f32 v[46:47], v[46:47], 1.0 op_sel_hi:[1,0]
	v_rcp_f32_e32 v44, v44
	v_rcp_f32_e32 v46, v46
	v_rcp_f32_e32 v47, v47
	v_rcp_f32_e32 v45, v45
	ds_bpermute_b32 v50, v164, v48
	v_pk_mul_f32 v[40:41], v[40:41], v[46:47]
	v_pk_mul_f32 v[42:43], v[42:43], v[44:45]
	s_nop 0
	v_pk_mul_f32 v[42:43], v[34:35], v[42:43]
	v_pk_mul_f32 v[34:35], v[32:33], v[40:41]
	s_waitcnt lgkmcnt(0)
; __device__ __forceinline__ v4u pack8(const float* x) { v4u o; o.x = pk2(x[0], x[1]); o.y = pk2(x[2], x[3]); o.z = pk2(x[4], x[5]); o.w = pk2(x[6], x[7]); return o; }
; __device__ __forceinline__ size_t tl(int row, int col, int K) { return (size_t)(row >> 8) * ((size_t)256 * K) + (size_t)(col >> 6) * (256 * 64) + (size_t)((row & 255) * 64 + (col & 63)); }
;     __device__ __forceinline__ void operator()(const f32x4 (&acc)[2][2][4][2], const Unit& u, int wr, int wc, int, int) const {
;     ...
;                 const int row = row0 + ai * HALF + m * 16; const float rs = rstd_from_quarter(pq[ai][m], fq * 16 + fr);
;                 float h[8];
; #pragma unroll
;                 for (int n = 0; n < 2; ++n) { const f32x4 g = acc[ai][0][m][n] * rs, uu = acc[ai][1][m][n] * rs; const f32x4 hv = (g * sigmoid4(g)) * uu;
;                     h[n * 4 + 0] = hv[0]; h[n * 4 + 1] = hv[1]; h[n * 4 + 2] = hv[2]; h[n * 4 + 3] = hv[3]; }
;                 __builtin_nontemporal_store(pack8(h), (u32x4*)(O + tl(row, col0, FF)));
	v_pk_add_f32 v[32:33], v[48:49], v[50:51]
	v_cvt_pk_bf16_f32 v34, v34, v35
	v_pk_fma_f32 v[40:41], v[32:33], s[74:75], v[156:157] op_sel_hi:[1,0,0]
	v_cvt_pk_bf16_f32 v33, v38, v39
	v_mul_f32_e32 v32, 0x4b800000, v41
	v_cmp_gt_f32_e32 vcc, s25, v41
	s_nop 1
	v_cndmask_b32_e32 v32, v41, v32, vcc
	v_rsq_f32_e32 v41, v32
	v_cvt_pk_bf16_f32 v32, v36, v37
	v_mul_f32_e32 v35, 0x45800000, v41
	v_cndmask_b32_e32 v36, v41, v35, vcc
	v_pk_mul_f32 v[28:29], v[28:29], v[36:37] op_sel_hi:[1,0]
	v_pk_mul_f32 v[30:31], v[30:31], v[36:37] op_sel_hi:[1,0]
	v_pk_mul_f32 v[44:45], v[28:29], s[38:39] op_sel_hi:[1,0]
	v_pk_mul_f32 v[38:39], v[30:31], s[38:39] op_sel_hi:[1,0]
	v_exp_f32_e32 v44, v44
	v_exp_f32_e32 v38, v38
	v_exp_f32_e32 v39, v39
	v_exp_f32_e32 v45, v45
	v_cvt_pk_bf16_f32 v35, v42, v43
	global_store_dwordx4 v[60:61], v[32:35], off offset:2048 nt
	v_pk_mul_f32 v[24:25], v[24:25], v[36:37] op_sel_hi:[1,0]
	v_pk_mul_f32 v[26:27], v[26:27], v[36:37] op_sel_hi:[1,0]
	v_pk_add_f32 v[32:33], v[38:39], 1.0 op_sel_hi:[1,0]
	v_pk_add_f32 v[34:35], v[44:45], 1.0 op_sel_hi:[1,0]
	v_rcp_f32_e32 v32, v32
	v_rcp_f32_e32 v34, v34
	v_rcp_f32_e32 v35, v35
	v_rcp_f32_e32 v33, v33
	v_pk_mul_f32 v[20:21], v[20:21], v[36:37] op_sel_hi:[1,0]
	v_pk_mul_f32 v[22:23], v[22:23], v[36:37] op_sel_hi:[1,0]
	v_pk_mul_f32 v[28:29], v[28:29], v[34:35]
	v_pk_mul_f32 v[30:31], v[30:31], v[32:33]
	v_pk_mul_f32 v[32:33], v[26:27], s[38:39] op_sel_hi:[1,0]
	v_pk_mul_f32 v[34:35], v[24:25], s[38:39] op_sel_hi:[1,0]
	v_exp_f32_e32 v32, v32
	v_exp_f32_e32 v34, v34
	v_exp_f32_e32 v33, v33
	v_exp_f32_e32 v35, v35
	v_pk_mul_f32 v[22:23], v[22:23], v[30:31]
	v_pk_mul_f32 v[20:21], v[20:21], v[28:29]
	v_pk_add_f32 v[28:29], v[32:33], 1.0 op_sel_hi:[1,0]
	v_pk_add_f32 v[30:31], v[34:35], 1.0 op_sel_hi:[1,0]
	v_rcp_f32_e32 v28, v28
	v_rcp_f32_e32 v30, v30
	v_rcp_f32_e32 v31, v31
	v_rcp_f32_e32 v29, v29
	v_pk_mul_f32 v[16:17], v[16:17], v[36:37] op_sel_hi:[1,0]
	v_pk_mul_f32 v[18:19], v[18:19], v[36:37] op_sel_hi:[1,0]
	v_pk_mul_f32 v[24:25], v[24:25], v[30:31]
	v_pk_mul_f32 v[26:27], v[26:27], v[28:29]
	v_cmp_gt_f32_e32 vcc, s25, v40
	v_pk_mul_f32 v[26:27], v[18:19], v[26:27]
	v_pk_mul_f32 v[18:19], v[16:17], v[24:25]
	v_mul_f32_e32 v17, 0x4b800000, v40
	v_cndmask_b32_e32 v17, v40, v17, vcc
	v_cvt_pk_bf16_f32 v16, v20, v21
	v_rsq_f32_e32 v20, v17
	v_cvt_pk_bf16_f32 v17, v22, v23
	v_cvt_pk_bf16_f32 v18, v18, v19
	v_cvt_pk_bf16_f32 v19, v26, v27
	v_mul_f32_e32 v21, 0x45800000, v20
	v_cndmask_b32_e32 v20, v20, v21, vcc
	v_pk_mul_f32 v[12:13], v[12:13], v[20:21] op_sel_hi:[1,0]
	v_pk_mul_f32 v[14:15], v[14:15], v[20:21] op_sel_hi:[1,0]
	v_pk_mul_f32 v[24:25], v[12:13], s[38:39] op_sel_hi:[1,0]
	v_pk_mul_f32 v[22:23], v[14:15], s[38:39] op_sel_hi:[1,0]
	v_exp_f32_e32 v24, v24
	v_exp_f32_e32 v25, v25
	v_exp_f32_e32 v22, v22
	v_exp_f32_e32 v23, v23
	v_add_co_u32_e32 v26, vcc, s85, v60
	v_pk_mul_f32 v[8:9], v[8:9], v[20:21] op_sel_hi:[1,0]
	s_nop 0
	v_addc_co_u32_e32 v27, vcc, 0, v61, vcc
	global_store_dwordx4 v[26:27], v[16:19], off nt
	v_pk_mul_f32 v[10:11], v[10:11], v[20:21] op_sel_hi:[1,0]
	v_pk_mul_f32 v[4:5], v[4:5], v[20:21] op_sel_hi:[1,0]
	v_pk_add_f32 v[16:17], v[22:23], 1.0 op_sel_hi:[1,0]
	v_pk_add_f32 v[18:19], v[24:25], 1.0 op_sel_hi:[1,0]
	v_rcp_f32_e32 v16, v16
	v_rcp_f32_e32 v18, v18
	v_rcp_f32_e32 v19, v19
	v_rcp_f32_e32 v17, v17
	v_pk_mul_f32 v[6:7], v[6:7], v[20:21] op_sel_hi:[1,0]
	v_pk_mul_f32 v[0:1], v[0:1], v[20:21] op_sel_hi:[1,0]
	v_pk_mul_f32 v[12:13], v[12:13], v[18:19]
	v_pk_mul_f32 v[14:15], v[14:15], v[16:17]
	v_pk_mul_f32 v[16:17], v[10:11], s[38:39] op_sel_hi:[1,0]
	v_pk_mul_f32 v[18:19], v[8:9], s[38:39] op_sel_hi:[1,0]
	v_exp_f32_e32 v16, v16
	v_exp_f32_e32 v18, v18
	v_exp_f32_e32 v17, v17
	v_exp_f32_e32 v19, v19
	v_pk_mul_f32 v[6:7], v[6:7], v[14:15]
	v_pk_mul_f32 v[4:5], v[4:5], v[12:13]
	v_pk_add_f32 v[12:13], v[16:17], 1.0 op_sel_hi:[1,0]
	v_pk_add_f32 v[14:15], v[18:19], 1.0 op_sel_hi:[1,0]
	v_rcp_f32_e32 v12, v12
	v_rcp_f32_e32 v14, v14
	v_rcp_f32_e32 v15, v15
	v_rcp_f32_e32 v13, v13
	v_pk_mul_f32 v[2:3], v[2:3], v[20:21] op_sel_hi:[1,0]
	s_andn2_b64 vcc, exec, s[2:3]
	v_pk_mul_f32 v[8:9], v[8:9], v[14:15]
	v_pk_mul_f32 v[10:11], v[10:11], v[12:13]
	s_mov_b64 s[2:3], -1
	v_pk_mul_f32 v[10:11], v[2:3], v[10:11]
	v_pk_mul_f32 v[2:3], v[0:1], v[8:9]
	v_cvt_pk_bf16_f32 v0, v4, v5
	v_cvt_pk_bf16_f32 v1, v6, v7
	v_cvt_pk_bf16_f32 v2, v2, v3
	v_cvt_pk_bf16_f32 v3, v10, v11
	global_store_dwordx4 v[26:27], v[0:3], off offset:2048 nt
	s_cbranch_vccnz .LBB0_1352
	s_andn2_b64 vcc, exec, s[0:1]
	s_cbranch_vccnz .LBB0_1351
	s_barrier
	s_branch .LBB0_1351
